# batched hand-written LN-stats prologue in FFN-in epilogue; transposed K/V stores through per-wave LDS transpose (64 B contiguous per row); NAT next-item query-row touch
# speedup vs baseline: 1.0358x; 1.0042x over previous
; __device__ __forceinline__ unsigned cvt_pk_bf16(float lo, float hi) { const f32x2_t f = {lo, hi}; const bf16x2_t v = __builtin_convertvector(f, bf16x2_t); return __builtin_bit_cast(unsigned, v); }
; __device__ __forceinline__ u32x4 pack8(const f32x4 a, const f32x4 b) { u32x4 w; w.x = cvt_pk_bf16(a[0], a[1]); w.y = cvt_pk_bf16(a[2], a[3]); w.z = cvt_pk_bf16(b[0], b[1]); w.w = cvt_pk_bf16(b[2], b[3]); return w; }
; __device__ __forceinline__ void store_T8(bf16_t* p, const f32x4 a, const f32x4 b, const int odd) {
;     bf16_t* q = odd ? p + 4 * (size_t)SEQ - 1 : p;
; #pragma unroll
;     for (int j = 0; j < 4; ++j) {
;         const float pa = __shfl_xor(a[j], 1), pb = __shfl_xor(b[j], 1);
;         *(unsigned*)(q + (size_t)j * SEQ) = odd ? cvt_pk_bf16(pb, b[j]) : cvt_pk_bf16(a[j], pa);
;     }
; }
;     __device__ __forceinline__ void operator()(const f32x4 (&acc)[2][2][4][2], const Unit& u, int wr, int wc, int fr_, int fq_) const {
;     ...
;                 for (int bj = 0; bj < 2; ++bj) {
;                     const f32x4 v0 = (acc[ai][bj][m][0] - mu * c1v[bj][0]) * rs + c2v[bj][0];
;                     const f32x4 v1 = (acc[ai][bj][m][1] - mu * c1v[bj][1]) * rs + c2v[bj][1];
;                     const int col = bj * 128 + lc;
;                     if (pn == 12) { if (col < 32) { *(f32x4*)(LR + (size_t)grow * 32 + col) = v0; *(f32x4*)(LR + (size_t)grow * 32 + col + 4) = v1; } }
;                     else {
;                         if (isP) *(u32x4*)(P + (size_t)grow * 2048 + pcol0 + col) = pack8(v0, v1);
;                         if (isT) store_T8(tb[bj] + tok, v0, v1, fr & 1);
;                     }
.LBB0_238:
	s_andn2_b64 vcc, exec, s[60:61]
	s_cbranch_vccnz .LBB0_240
	v_mov_b32_dpp v187, v160 quad_perm:[1,0,3,2] row_mask:0xf bank_mask:0xf
	v_mov_b32_dpp v188, v156 quad_perm:[1,0,3,2] row_mask:0xf bank_mask:0xf
	v_cndmask_b32_e64 v160, v188, v160, s[42:43]
	v_cndmask_b32_e64 v156, v156, v187, s[42:43]
	v_cvt_pk_bf16_f32 v160, v160, v156
	v_mov_b32_dpp v187, v161 quad_perm:[1,0,3,2] row_mask:0xf bank_mask:0xf
	v_mov_b32_dpp v188, v157 quad_perm:[1,0,3,2] row_mask:0xf bank_mask:0xf
	v_cndmask_b32_e64 v161, v188, v161, s[42:43]
	v_cndmask_b32_e64 v157, v157, v187, s[42:43]
	v_cvt_pk_bf16_f32 v161, v161, v157
	v_mov_b32_dpp v187, v162 quad_perm:[1,0,3,2] row_mask:0xf bank_mask:0xf
	v_mov_b32_dpp v188, v158 quad_perm:[1,0,3,2] row_mask:0xf bank_mask:0xf
	v_cndmask_b32_e64 v162, v188, v162, s[42:43]
	v_cndmask_b32_e64 v158, v158, v187, s[42:43]
	v_cvt_pk_bf16_f32 v162, v162, v158
	v_mov_b32_dpp v187, v163 quad_perm:[1,0,3,2] row_mask:0xf bank_mask:0xf
	v_mov_b32_dpp v188, v159 quad_perm:[1,0,3,2] row_mask:0xf bank_mask:0xf
	v_cndmask_b32_e64 v163, v188, v163, s[42:43]
	v_cndmask_b32_e64 v159, v159, v187, s[42:43]
	v_cvt_pk_bf16_f32 v163, v163, v159
	v_lshrrev_b32_e32 v187, 6, v250
	v_mul_u32_u24_e32 v187, 0xc00, v187
	v_and_b32_e32 v188, 48, v231
	v_lshl_add_u32 v187, v188, 4, v187
	v_add_u32_e32 v187, 0x20400, v187
	v_and_b32_e32 v188, 1, v231
	v_lshl_add_u32 v194, v188, 7, v187
	v_and_b32_e32 v188, 14, v231
	v_lshl_add_u32 v194, v188, 1, v194
	ds_write_b32 v194, v160 offset:0
	ds_write_b32 v194, v161 offset:32
	ds_write_b32 v194, v162 offset:64
	ds_write_b32 v194, v163 offset:96

; __device__ __forceinline__ unsigned cvt_pk_bf16(float lo, float hi) { const f32x2_t f = {lo, hi}; const bf16x2_t v = __builtin_convertvector(f, bf16x2_t); return __builtin_bit_cast(unsigned, v); }
; __device__ __forceinline__ u32x4 pack8(const f32x4 a, const f32x4 b) { u32x4 w; w.x = cvt_pk_bf16(a[0], a[1]); w.y = cvt_pk_bf16(a[2], a[3]); w.z = cvt_pk_bf16(b[0], b[1]); w.w = cvt_pk_bf16(b[2], b[3]); return w; }
; __device__ __forceinline__ void store_T8(bf16_t* p, const f32x4 a, const f32x4 b, const int odd) {
;     bf16_t* q = odd ? p + 4 * (size_t)SEQ - 1 : p;
; #pragma unroll
;     for (int j = 0; j < 4; ++j) {
;         const float pa = __shfl_xor(a[j], 1), pb = __shfl_xor(b[j], 1);
;         *(unsigned*)(q + (size_t)j * SEQ) = odd ? cvt_pk_bf16(pb, b[j]) : cvt_pk_bf16(a[j], pa);
;     }
; }
;     __device__ __forceinline__ void operator()(const f32x4 (&acc)[2][2][4][2], const Unit& u, int wr, int wc, int fr_, int fq_) const {
;     ...
;                 for (int bj = 0; bj < 2; ++bj) {
;                     const f32x4 v0 = (acc[ai][bj][m][0] - mu * c1v[bj][0]) * rs + c2v[bj][0];
;                     const f32x4 v1 = (acc[ai][bj][m][1] - mu * c1v[bj][1]) * rs + c2v[bj][1];
;                     const int col = bj * 128 + lc;
;                     if (pn == 12) { if (col < 32) { *(f32x4*)(LR + (size_t)grow * 32 + col) = v0; *(f32x4*)(LR + (size_t)grow * 32 + col + 4) = v1; } }
;                     else {
;                         if (isP) *(u32x4*)(P + (size_t)grow * 2048 + pcol0 + col) = pack8(v0, v1);
;                         if (isT) store_T8(tb[bj] + tok, v0, v1, fr & 1);
;                     }
.LBB0_248:
	s_andn2_b64 vcc, exec, s[60:61]
	s_cbranch_vccnz .LBB0_250
	v_mov_b32_dpp v158, v152 quad_perm:[1,0,3,2] row_mask:0xf bank_mask:0xf
	v_mov_b32_dpp v160, v148 quad_perm:[1,0,3,2] row_mask:0xf bank_mask:0xf
	v_cndmask_b32_e64 v152, v160, v152, s[42:43]
	v_cndmask_b32_e64 v148, v148, v158, s[42:43]
	v_cvt_pk_bf16_f32 v152, v152, v148
	v_mov_b32_dpp v158, v153 quad_perm:[1,0,3,2] row_mask:0xf bank_mask:0xf
	v_mov_b32_dpp v160, v149 quad_perm:[1,0,3,2] row_mask:0xf bank_mask:0xf
	v_cndmask_b32_e64 v153, v160, v153, s[42:43]
	v_cndmask_b32_e64 v149, v149, v158, s[42:43]
	v_cvt_pk_bf16_f32 v153, v153, v149
	v_mov_b32_dpp v158, v154 quad_perm:[1,0,3,2] row_mask:0xf bank_mask:0xf
	v_mov_b32_dpp v160, v150 quad_perm:[1,0,3,2] row_mask:0xf bank_mask:0xf
	v_cndmask_b32_e64 v154, v160, v154, s[42:43]
	v_cndmask_b32_e64 v150, v150, v158, s[42:43]
	v_cvt_pk_bf16_f32 v154, v154, v150
	v_mov_b32_dpp v158, v155 quad_perm:[1,0,3,2] row_mask:0xf bank_mask:0xf
	v_mov_b32_dpp v160, v151 quad_perm:[1,0,3,2] row_mask:0xf bank_mask:0xf
	v_cndmask_b32_e64 v155, v160, v155, s[42:43]
	v_cndmask_b32_e64 v151, v151, v158, s[42:43]
	v_cvt_pk_bf16_f32 v155, v155, v151
	v_lshrrev_b32_e32 v158, 6, v250
	v_mul_u32_u24_e32 v158, 0xc00, v158
	v_and_b32_e32 v160, 48, v231
	v_lshl_add_u32 v158, v160, 4, v158
	v_add_u32_e32 v158, 0x20400, v158
	v_and_b32_e32 v160, 1, v231
	v_lshl_add_u32 v159, v160, 7, v158
	v_and_b32_e32 v160, 14, v231
	v_lshl_add_u32 v159, v160, 1, v159
	v_add_u32_e32 v159, 1024, v159
	ds_write_b32 v159, v152 offset:0
	ds_write_b32 v159, v153 offset:32
	ds_write_b32 v159, v154 offset:64
	ds_write_b32 v159, v155 offset:96

; __device__ __forceinline__ unsigned cvt_pk_bf16(float lo, float hi) { const f32x2_t f = {lo, hi}; const bf16x2_t v = __builtin_convertvector(f, bf16x2_t); return __builtin_bit_cast(unsigned, v); }
; __device__ __forceinline__ u32x4 pack8(const f32x4 a, const f32x4 b) { u32x4 w; w.x = cvt_pk_bf16(a[0], a[1]); w.y = cvt_pk_bf16(a[2], a[3]); w.z = cvt_pk_bf16(b[0], b[1]); w.w = cvt_pk_bf16(b[2], b[3]); return w; }
; __device__ __forceinline__ void store_T8(bf16_t* p, const f32x4 a, const f32x4 b, const int odd) {
;     bf16_t* q = odd ? p + 4 * (size_t)SEQ - 1 : p;
; #pragma unroll
;     for (int j = 0; j < 4; ++j) {
;         const float pa = __shfl_xor(a[j], 1), pb = __shfl_xor(b[j], 1);
;         *(unsigned*)(q + (size_t)j * SEQ) = odd ? cvt_pk_bf16(pb, b[j]) : cvt_pk_bf16(a[j], pa);
;     }
; }
;     __device__ __forceinline__ void operator()(const f32x4 (&acc)[2][2][4][2], const Unit& u, int wr, int wc, int fr_, int fq_) const {
;     ...
;                 for (int bj = 0; bj < 2; ++bj) {
;                     const f32x4 v0 = (acc[ai][bj][m][0] - mu * c1v[bj][0]) * rs + c2v[bj][0];
;                     const f32x4 v1 = (acc[ai][bj][m][1] - mu * c1v[bj][1]) * rs + c2v[bj][1];
;                     const int col = bj * 128 + lc;
;                     if (pn == 12) { if (col < 32) { *(f32x4*)(LR + (size_t)grow * 32 + col) = v0; *(f32x4*)(LR + (size_t)grow * 32 + col + 4) = v1; } }
;                     else {
;                         if (isP) *(u32x4*)(P + (size_t)grow * 2048 + pcol0 + col) = pack8(v0, v1);
;                         if (isT) store_T8(tb[bj] + tok, v0, v1, fr & 1);
;                     }
.LBB0_258:
	s_andn2_b64 vcc, exec, s[60:61]
	s_cbranch_vccnz .LBB0_260
	v_mov_b32_dpp v144, v140 quad_perm:[1,0,3,2] row_mask:0xf bank_mask:0xf
	v_mov_b32_dpp v154, v136 quad_perm:[1,0,3,2] row_mask:0xf bank_mask:0xf
	v_cndmask_b32_e64 v140, v154, v140, s[42:43]
	v_cndmask_b32_e64 v136, v136, v144, s[42:43]
	v_cvt_pk_bf16_f32 v140, v140, v136
	v_mov_b32_dpp v144, v141 quad_perm:[1,0,3,2] row_mask:0xf bank_mask:0xf
	v_mov_b32_dpp v154, v137 quad_perm:[1,0,3,2] row_mask:0xf bank_mask:0xf
	v_cndmask_b32_e64 v141, v154, v141, s[42:43]
	v_cndmask_b32_e64 v137, v137, v144, s[42:43]
	v_cvt_pk_bf16_f32 v141, v141, v137
	v_mov_b32_dpp v144, v142 quad_perm:[1,0,3,2] row_mask:0xf bank_mask:0xf
	v_mov_b32_dpp v154, v138 quad_perm:[1,0,3,2] row_mask:0xf bank_mask:0xf
	v_cndmask_b32_e64 v142, v154, v142, s[42:43]
	v_cndmask_b32_e64 v138, v138, v144, s[42:43]
	v_cvt_pk_bf16_f32 v142, v142, v138
	v_mov_b32_dpp v144, v143 quad_perm:[1,0,3,2] row_mask:0xf bank_mask:0xf
	v_mov_b32_dpp v154, v139 quad_perm:[1,0,3,2] row_mask:0xf bank_mask:0xf
	v_cndmask_b32_e64 v143, v154, v143, s[42:43]
	v_cndmask_b32_e64 v139, v139, v144, s[42:43]
	v_cvt_pk_bf16_f32 v143, v143, v139
	v_lshrrev_b32_e32 v144, 6, v250
	v_mul_u32_u24_e32 v144, 0xc00, v144
	v_and_b32_e32 v154, 48, v231
	v_lshl_add_u32 v144, v154, 4, v144
	v_add_u32_e32 v144, 0x20400, v144
	v_and_b32_e32 v154, 1, v231
	v_lshl_add_u32 v155, v154, 7, v144
	v_and_b32_e32 v154, 14, v231
	v_lshl_add_u32 v155, v154, 1, v155
	v_add_u32_e32 v155, 2048, v155
	ds_write_b32 v155, v140 offset:0
	ds_write_b32 v155, v141 offset:32
	ds_write_b32 v155, v142 offset:64
	ds_write_b32 v155, v143 offset:96
	v_and_b32_e32 v154, 15, v231
	v_lshrrev_b32_e32 v155, 2, v154
	v_lshl_add_u32 v144, v155, 5, v144
	v_and_b32_e32 v155, 1, v154
	v_lshl_add_u32 v144, v155, 4, v144
	v_bfe_u32 v155, v154, 1, 1
	v_mul_u32_u24_e32 v155, 2048, v155
	v_add_u32_e32 v144, v144, v155
	v_and_b32_e32 v159, 3, v154
	v_lshlrev_b32_e32 v159, 3, v159
	v_sub_u32_e32 v159, v159, v154
	v_add_u32_e32 v159, -16, v159
	v_lshlrev_b32_e32 v159, 1, v159
	v_lshrrev_b32_e32 v154, 2, v154
	v_lshl_add_u32 v155, v154, 12, v159
	v_ashrrev_i32_e32 v159, 31, v155
	v_lshl_add_u64 v[152:153], v[38:39], 1, v[164:165]
	v_add_co_u32_e32 v152, vcc, v155, v152
	s_nop 1
	v_addc_co_u32_e32 v153, vcc, v159, v153, vcc
	s_waitcnt lgkmcnt(0)
	ds_read_b128 v[136:139], v144
	ds_read_b128 v[140:143], v144 offset:128
	s_waitcnt lgkmcnt(1)
	global_store_dwordx4 v[152:153], v[136:139], off
	v_add_co_u32_e32 v152, vcc, 0x4000, v152
	s_nop 1
	v_addc_co_u32_e32 v153, vcc, 0, v153, vcc
	s_waitcnt lgkmcnt(0)
	global_store_dwordx4 v[152:153], v[140:143], off
	s_nop 1

; __device__ __forceinline__ unsigned cvt_pk_bf16(float lo, float hi) { const f32x2_t f = {lo, hi}; const bf16x2_t v = __builtin_convertvector(f, bf16x2_t); return __builtin_bit_cast(unsigned, v); }
; __device__ __forceinline__ u32x4 pack8(const f32x4 a, const f32x4 b) { u32x4 w; w.x = cvt_pk_bf16(a[0], a[1]); w.y = cvt_pk_bf16(a[2], a[3]); w.z = cvt_pk_bf16(b[0], b[1]); w.w = cvt_pk_bf16(b[2], b[3]); return w; }
; __device__ __forceinline__ void store_T8(bf16_t* p, const f32x4 a, const f32x4 b, const int odd) {
;     bf16_t* q = odd ? p + 4 * (size_t)SEQ - 1 : p;
; #pragma unroll
;     for (int j = 0; j < 4; ++j) {
;         const float pa = __shfl_xor(a[j], 1), pb = __shfl_xor(b[j], 1);
;         *(unsigned*)(q + (size_t)j * SEQ) = odd ? cvt_pk_bf16(pb, b[j]) : cvt_pk_bf16(a[j], pa);
;     }
; }
;     __device__ __forceinline__ void operator()(const f32x4 (&acc)[2][2][4][2], const Unit& u, int wr, int wc, int fr_, int fq_) const {
;     ...
;                 for (int bj = 0; bj < 2; ++bj) {
;                     const f32x4 v0 = (acc[ai][bj][m][0] - mu * c1v[bj][0]) * rs + c2v[bj][0];
;                     const f32x4 v1 = (acc[ai][bj][m][1] - mu * c1v[bj][1]) * rs + c2v[bj][1];
;                     const int col = bj * 128 + lc;
;                     if (pn == 12) { if (col < 32) { *(f32x4*)(LR + (size_t)grow * 32 + col) = v0; *(f32x4*)(LR + (size_t)grow * 32 + col + 4) = v1; } }
;                     else {
;                         if (isP) *(u32x4*)(P + (size_t)grow * 2048 + pcol0 + col) = pack8(v0, v1);
;                         if (isT) store_T8(tb[bj] + tok, v0, v1, fr & 1);
;                     }
.LBB0_268:
	s_andn2_b64 vcc, exec, s[60:61]
	s_cbranch_vccnz .LBB0_270
	v_mov_b32_dpp v136, v132 quad_perm:[1,0,3,2] row_mask:0xf bank_mask:0xf
	v_mov_b32_dpp v138, v128 quad_perm:[1,0,3,2] row_mask:0xf bank_mask:0xf
	v_cndmask_b32_e64 v132, v138, v132, s[42:43]
	v_cndmask_b32_e64 v128, v128, v136, s[42:43]
	v_cvt_pk_bf16_f32 v132, v132, v128
	v_mov_b32_dpp v136, v133 quad_perm:[1,0,3,2] row_mask:0xf bank_mask:0xf
	v_mov_b32_dpp v138, v129 quad_perm:[1,0,3,2] row_mask:0xf bank_mask:0xf
	v_cndmask_b32_e64 v133, v138, v133, s[42:43]
	v_cndmask_b32_e64 v129, v129, v136, s[42:43]
	v_cvt_pk_bf16_f32 v133, v133, v129
	v_mov_b32_dpp v136, v134 quad_perm:[1,0,3,2] row_mask:0xf bank_mask:0xf
	v_mov_b32_dpp v138, v130 quad_perm:[1,0,3,2] row_mask:0xf bank_mask:0xf
	v_cndmask_b32_e64 v134, v138, v134, s[42:43]
	v_cndmask_b32_e64 v130, v130, v136, s[42:43]
	v_cvt_pk_bf16_f32 v134, v134, v130
	v_mov_b32_dpp v136, v135 quad_perm:[1,0,3,2] row_mask:0xf bank_mask:0xf
	v_mov_b32_dpp v138, v131 quad_perm:[1,0,3,2] row_mask:0xf bank_mask:0xf
	v_cndmask_b32_e64 v135, v138, v135, s[42:43]
	v_cndmask_b32_e64 v131, v131, v136, s[42:43]
	v_cvt_pk_bf16_f32 v135, v135, v131
	v_lshrrev_b32_e32 v136, 6, v250
	v_mul_u32_u24_e32 v136, 0xc00, v136
	v_and_b32_e32 v138, 48, v231
	v_lshl_add_u32 v136, v138, 4, v136
	v_add_u32_e32 v136, 0x20400, v136
	v_and_b32_e32 v138, 1, v231
	v_lshl_add_u32 v137, v138, 7, v136
	v_and_b32_e32 v138, 14, v231
	v_lshl_add_u32 v137, v138, 1, v137
	v_add_u32_e32 v137, 2048, v137
	ds_write_b32 v137, v132 offset:0
	ds_write_b32 v137, v133 offset:32
	ds_write_b32 v137, v134 offset:64
	ds_write_b32 v137, v135 offset:96
	v_and_b32_e32 v138, 15, v231
	v_lshrrev_b32_e32 v137, 2, v138
	v_lshl_add_u32 v136, v137, 5, v136
	v_and_b32_e32 v137, 1, v138
	v_lshl_add_u32 v136, v137, 4, v136
	v_bfe_u32 v137, v138, 1, 1
	v_mul_u32_u24_e32 v137, 1024, v137
	v_add_u32_e32 v136, v136, v137
	v_add_u32_e32 v136, 1024, v136
	v_and_b32_e32 v140, 3, v138
	v_lshlrev_b32_e32 v140, 3, v140
	v_sub_u32_e32 v140, v140, v138
	v_add_u32_e32 v140, -16, v140
	v_lshlrev_b32_e32 v140, 1, v140
	v_lshrrev_b32_e32 v138, 2, v138
	v_lshl_add_u32 v137, v138, 12, v140
	v_ashrrev_i32_e32 v140, 31, v137
	v_lshl_add_u64 v[38:39], v[38:39], 1, v[58:59]
	v_add_co_u32_e32 v38, vcc, v137, v38
	s_nop 1
	v_addc_co_u32_e32 v39, vcc, v140, v39, vcc
	s_waitcnt lgkmcnt(0)
	ds_read_b128 v[128:131], v136
	ds_read_b128 v[132:135], v136 offset:128
	s_waitcnt lgkmcnt(1)
	global_store_dwordx4 v[38:39], v[128:131], off
	v_add_co_u32_e32 v38, vcc, 0x4000, v38
	s_nop 1
	v_addc_co_u32_e32 v39, vcc, 0, v39, vcc
	s_waitcnt lgkmcnt(0)
	global_store_dwordx4 v[38:39], v[132:135], off
	s_nop 1

; __device__ __forceinline__ unsigned cvt_pk_bf16(float lo, float hi) { const f32x2_t f = {lo, hi}; const bf16x2_t v = __builtin_convertvector(f, bf16x2_t); return __builtin_bit_cast(unsigned, v); }
; __device__ __forceinline__ u32x4 pack8(const f32x4 a, const f32x4 b) { u32x4 w; w.x = cvt_pk_bf16(a[0], a[1]); w.y = cvt_pk_bf16(a[2], a[3]); w.z = cvt_pk_bf16(b[0], b[1]); w.w = cvt_pk_bf16(b[2], b[3]); return w; }
; __device__ __forceinline__ void store_T8(bf16_t* p, const f32x4 a, const f32x4 b, const int odd) {
;     bf16_t* q = odd ? p + 4 * (size_t)SEQ - 1 : p;
; #pragma unroll
;     for (int j = 0; j < 4; ++j) {
;         const float pa = __shfl_xor(a[j], 1), pb = __shfl_xor(b[j], 1);
;         *(unsigned*)(q + (size_t)j * SEQ) = odd ? cvt_pk_bf16(pb, b[j]) : cvt_pk_bf16(a[j], pa);
;     }
; }
;     __device__ __forceinline__ void operator()(const f32x4 (&acc)[2][2][4][2], const Unit& u, int wr, int wc, int fr_, int fq_) const {
;     ...
;                 for (int bj = 0; bj < 2; ++bj) {
;                     const f32x4 v0 = (acc[ai][bj][m][0] - mu * c1v[bj][0]) * rs + c2v[bj][0];
;                     const f32x4 v1 = (acc[ai][bj][m][1] - mu * c1v[bj][1]) * rs + c2v[bj][1];
;                     const int col = bj * 128 + lc;
;                     if (pn == 12) { if (col < 32) { *(f32x4*)(LR + (size_t)grow * 32 + col) = v0; *(f32x4*)(LR + (size_t)grow * 32 + col + 4) = v1; } }
;                     else {
;                         if (isP) *(u32x4*)(P + (size_t)grow * 2048 + pcol0 + col) = pack8(v0, v1);
;                         if (isT) store_T8(tb[bj] + tok, v0, v1, fr & 1);
;                     }
.LBB0_278:
	s_andn2_b64 vcc, exec, s[60:61]
	s_cbranch_vccnz .LBB0_280
	v_mov_b32_dpp v134, v124 quad_perm:[1,0,3,2] row_mask:0xf bank_mask:0xf
	v_mov_b32_dpp v136, v120 quad_perm:[1,0,3,2] row_mask:0xf bank_mask:0xf
	v_cndmask_b32_e64 v124, v136, v124, s[42:43]
	v_cndmask_b32_e64 v120, v120, v134, s[42:43]
	v_cvt_pk_bf16_f32 v124, v124, v120
	v_mov_b32_dpp v134, v125 quad_perm:[1,0,3,2] row_mask:0xf bank_mask:0xf
	v_mov_b32_dpp v136, v121 quad_perm:[1,0,3,2] row_mask:0xf bank_mask:0xf
	v_cndmask_b32_e64 v125, v136, v125, s[42:43]
	v_cndmask_b32_e64 v121, v121, v134, s[42:43]
	v_cvt_pk_bf16_f32 v125, v125, v121
	v_mov_b32_dpp v134, v126 quad_perm:[1,0,3,2] row_mask:0xf bank_mask:0xf
	v_mov_b32_dpp v136, v122 quad_perm:[1,0,3,2] row_mask:0xf bank_mask:0xf
	v_cndmask_b32_e64 v126, v136, v126, s[42:43]
	v_cndmask_b32_e64 v122, v122, v134, s[42:43]
	v_cvt_pk_bf16_f32 v126, v126, v122
	v_mov_b32_dpp v134, v127 quad_perm:[1,0,3,2] row_mask:0xf bank_mask:0xf
	v_mov_b32_dpp v136, v123 quad_perm:[1,0,3,2] row_mask:0xf bank_mask:0xf
	v_cndmask_b32_e64 v127, v136, v127, s[42:43]
	v_cndmask_b32_e64 v123, v123, v134, s[42:43]
	v_cvt_pk_bf16_f32 v127, v127, v123
	v_lshrrev_b32_e32 v134, 6, v250
	v_mul_u32_u24_e32 v134, 0xc00, v134
	v_and_b32_e32 v136, 48, v231
	v_lshl_add_u32 v134, v136, 4, v134
	v_add_u32_e32 v134, 0x20400, v134
	v_and_b32_e32 v136, 1, v231
	v_lshl_add_u32 v135, v136, 7, v134
	v_and_b32_e32 v136, 14, v231
	v_lshl_add_u32 v135, v136, 1, v135
	ds_write_b32 v135, v124 offset:0
	ds_write_b32 v135, v125 offset:32
	ds_write_b32 v135, v126 offset:64
	ds_write_b32 v135, v127 offset:96

; __device__ __forceinline__ unsigned cvt_pk_bf16(float lo, float hi) { const f32x2_t f = {lo, hi}; const bf16x2_t v = __builtin_convertvector(f, bf16x2_t); return __builtin_bit_cast(unsigned, v); }
; __device__ __forceinline__ u32x4 pack8(const f32x4 a, const f32x4 b) { u32x4 w; w.x = cvt_pk_bf16(a[0], a[1]); w.y = cvt_pk_bf16(a[2], a[3]); w.z = cvt_pk_bf16(b[0], b[1]); w.w = cvt_pk_bf16(b[2], b[3]); return w; }
; __device__ __forceinline__ void store_T8(bf16_t* p, const f32x4 a, const f32x4 b, const int odd) {
;     bf16_t* q = odd ? p + 4 * (size_t)SEQ - 1 : p;
; #pragma unroll
;     for (int j = 0; j < 4; ++j) {
;         const float pa = __shfl_xor(a[j], 1), pb = __shfl_xor(b[j], 1);
;         *(unsigned*)(q + (size_t)j * SEQ) = odd ? cvt_pk_bf16(pb, b[j]) : cvt_pk_bf16(a[j], pa);
;     }
; }
;     __device__ __forceinline__ void operator()(const f32x4 (&acc)[2][2][4][2], const Unit& u, int wr, int wc, int fr_, int fq_) const {
;     ...
;                 for (int bj = 0; bj < 2; ++bj) {
;                     const f32x4 v0 = (acc[ai][bj][m][0] - mu * c1v[bj][0]) * rs + c2v[bj][0];
;                     const f32x4 v1 = (acc[ai][bj][m][1] - mu * c1v[bj][1]) * rs + c2v[bj][1];
;                     const int col = bj * 128 + lc;
;                     if (pn == 12) { if (col < 32) { *(f32x4*)(LR + (size_t)grow * 32 + col) = v0; *(f32x4*)(LR + (size_t)grow * 32 + col + 4) = v1; } }
;                     else {
;                         if (isP) *(u32x4*)(P + (size_t)grow * 2048 + pcol0 + col) = pack8(v0, v1);
;                         if (isT) store_T8(tb[bj] + tok, v0, v1, fr & 1);
;                     }
.LBB0_288:
	s_andn2_b64 vcc, exec, s[60:61]
	s_cbranch_vccnz .LBB0_290
	v_mov_b32_dpp v120, v116 quad_perm:[1,0,3,2] row_mask:0xf bank_mask:0xf
	v_mov_b32_dpp v122, v112 quad_perm:[1,0,3,2] row_mask:0xf bank_mask:0xf
	v_cndmask_b32_e64 v116, v122, v116, s[42:43]
	v_cndmask_b32_e64 v112, v112, v120, s[42:43]
	v_cvt_pk_bf16_f32 v116, v116, v112
	v_mov_b32_dpp v120, v117 quad_perm:[1,0,3,2] row_mask:0xf bank_mask:0xf
	v_mov_b32_dpp v122, v113 quad_perm:[1,0,3,2] row_mask:0xf bank_mask:0xf
	v_cndmask_b32_e64 v117, v122, v117, s[42:43]
	v_cndmask_b32_e64 v113, v113, v120, s[42:43]
	v_cvt_pk_bf16_f32 v117, v117, v113
	v_mov_b32_dpp v120, v118 quad_perm:[1,0,3,2] row_mask:0xf bank_mask:0xf
	v_mov_b32_dpp v122, v114 quad_perm:[1,0,3,2] row_mask:0xf bank_mask:0xf
	v_cndmask_b32_e64 v118, v122, v118, s[42:43]
	v_cndmask_b32_e64 v114, v114, v120, s[42:43]
	v_cvt_pk_bf16_f32 v118, v118, v114
	v_mov_b32_dpp v120, v119 quad_perm:[1,0,3,2] row_mask:0xf bank_mask:0xf
	v_mov_b32_dpp v122, v115 quad_perm:[1,0,3,2] row_mask:0xf bank_mask:0xf
	v_cndmask_b32_e64 v119, v122, v119, s[42:43]
	v_cndmask_b32_e64 v115, v115, v120, s[42:43]
	v_cvt_pk_bf16_f32 v119, v119, v115
	v_lshrrev_b32_e32 v120, 6, v250
	v_mul_u32_u24_e32 v120, 0xc00, v120
	v_and_b32_e32 v122, 48, v231
	v_lshl_add_u32 v120, v122, 4, v120
	v_add_u32_e32 v120, 0x20400, v120
	v_and_b32_e32 v122, 1, v231
	v_lshl_add_u32 v121, v122, 7, v120
	v_and_b32_e32 v122, 14, v231
	v_lshl_add_u32 v121, v122, 1, v121
	v_add_u32_e32 v121, 1024, v121
	ds_write_b32 v121, v116 offset:0
	ds_write_b32 v121, v117 offset:32
	ds_write_b32 v121, v118 offset:64
	ds_write_b32 v121, v119 offset:96

; __device__ __forceinline__ unsigned cvt_pk_bf16(float lo, float hi) { const f32x2_t f = {lo, hi}; const bf16x2_t v = __builtin_convertvector(f, bf16x2_t); return __builtin_bit_cast(unsigned, v); }
; __device__ __forceinline__ u32x4 pack8(const f32x4 a, const f32x4 b) { u32x4 w; w.x = cvt_pk_bf16(a[0], a[1]); w.y = cvt_pk_bf16(a[2], a[3]); w.z = cvt_pk_bf16(b[0], b[1]); w.w = cvt_pk_bf16(b[2], b[3]); return w; }
; __device__ __forceinline__ void store_T8(bf16_t* p, const f32x4 a, const f32x4 b, const int odd) {
;     bf16_t* q = odd ? p + 4 * (size_t)SEQ - 1 : p;
; #pragma unroll
;     for (int j = 0; j < 4; ++j) {
;         const float pa = __shfl_xor(a[j], 1), pb = __shfl_xor(b[j], 1);
;         *(unsigned*)(q + (size_t)j * SEQ) = odd ? cvt_pk_bf16(pb, b[j]) : cvt_pk_bf16(a[j], pa);
;     }
; }
;     __device__ __forceinline__ void operator()(const f32x4 (&acc)[2][2][4][2], const Unit& u, int wr, int wc, int fr_, int fq_) const {
;     ...
;                 for (int bj = 0; bj < 2; ++bj) {
;                     const f32x4 v0 = (acc[ai][bj][m][0] - mu * c1v[bj][0]) * rs + c2v[bj][0];
;                     const f32x4 v1 = (acc[ai][bj][m][1] - mu * c1v[bj][1]) * rs + c2v[bj][1];
;                     const int col = bj * 128 + lc;
;                     if (pn == 12) { if (col < 32) { *(f32x4*)(LR + (size_t)grow * 32 + col) = v0; *(f32x4*)(LR + (size_t)grow * 32 + col + 4) = v1; } }
;                     else {
;                         if (isP) *(u32x4*)(P + (size_t)grow * 2048 + pcol0 + col) = pack8(v0, v1);
;                         if (isT) store_T8(tb[bj] + tok, v0, v1, fr & 1);
;                     }
.LBB0_298:
	s_andn2_b64 vcc, exec, s[60:61]
	s_cbranch_vccnz .LBB0_300
	v_mov_b32_dpp v118, v108 quad_perm:[1,0,3,2] row_mask:0xf bank_mask:0xf
	v_mov_b32_dpp v120, v104 quad_perm:[1,0,3,2] row_mask:0xf bank_mask:0xf
	v_cndmask_b32_e64 v108, v120, v108, s[42:43]
	v_cndmask_b32_e64 v104, v104, v118, s[42:43]
	v_cvt_pk_bf16_f32 v108, v108, v104
	v_mov_b32_dpp v118, v109 quad_perm:[1,0,3,2] row_mask:0xf bank_mask:0xf
	v_mov_b32_dpp v120, v105 quad_perm:[1,0,3,2] row_mask:0xf bank_mask:0xf
	v_cndmask_b32_e64 v109, v120, v109, s[42:43]
	v_cndmask_b32_e64 v105, v105, v118, s[42:43]
	v_cvt_pk_bf16_f32 v109, v109, v105
	v_mov_b32_dpp v118, v110 quad_perm:[1,0,3,2] row_mask:0xf bank_mask:0xf
	v_mov_b32_dpp v120, v106 quad_perm:[1,0,3,2] row_mask:0xf bank_mask:0xf
	v_cndmask_b32_e64 v110, v120, v110, s[42:43]
	v_cndmask_b32_e64 v106, v106, v118, s[42:43]
	v_cvt_pk_bf16_f32 v110, v110, v106
	v_mov_b32_dpp v118, v111 quad_perm:[1,0,3,2] row_mask:0xf bank_mask:0xf
	v_mov_b32_dpp v120, v107 quad_perm:[1,0,3,2] row_mask:0xf bank_mask:0xf
	v_cndmask_b32_e64 v111, v120, v111, s[42:43]
	v_cndmask_b32_e64 v107, v107, v118, s[42:43]
	v_cvt_pk_bf16_f32 v111, v111, v107
	v_lshrrev_b32_e32 v118, 6, v250
	v_mul_u32_u24_e32 v118, 0xc00, v118
	v_and_b32_e32 v120, 48, v231
	v_lshl_add_u32 v118, v120, 4, v118
	v_add_u32_e32 v118, 0x20400, v118
	v_and_b32_e32 v120, 1, v231
	v_lshl_add_u32 v119, v120, 7, v118
	v_and_b32_e32 v120, 14, v231
	v_lshl_add_u32 v119, v120, 1, v119
	v_add_u32_e32 v119, 2048, v119
	ds_write_b32 v119, v108 offset:0
	ds_write_b32 v119, v109 offset:32
	ds_write_b32 v119, v110 offset:64
	ds_write_b32 v119, v111 offset:96
	v_and_b32_e32 v120, 15, v231
	v_lshrrev_b32_e32 v119, 2, v120
	v_lshl_add_u32 v118, v119, 5, v118
	v_and_b32_e32 v119, 1, v120
	v_lshl_add_u32 v118, v119, 4, v118
	v_bfe_u32 v119, v120, 1, 1
	v_mul_u32_u24_e32 v119, 2048, v119
	v_add_u32_e32 v118, v118, v119
	v_and_b32_e32 v122, 3, v120
	v_lshlrev_b32_e32 v122, 3, v122
	v_sub_u32_e32 v122, v122, v120
	v_add_u32_e32 v122, -16, v122
	v_lshlrev_b32_e32 v122, 1, v122
	v_lshrrev_b32_e32 v120, 2, v120
	v_lshl_add_u32 v119, v120, 12, v122
	v_ashrrev_i32_e32 v122, 31, v119
	v_lshl_add_u64 v[116:117], v[38:39], 1, v[164:165]
	v_add_co_u32_e32 v116, vcc, v119, v116
	s_nop 1
	v_addc_co_u32_e32 v117, vcc, v122, v117, vcc
	s_waitcnt lgkmcnt(0)
	ds_read_b128 v[104:107], v118
	ds_read_b128 v[108:111], v118 offset:128
	s_waitcnt lgkmcnt(1)
	global_store_dwordx4 v[116:117], v[104:107], off
	v_add_co_u32_e32 v116, vcc, 0x4000, v116
	s_nop 1
	v_addc_co_u32_e32 v117, vcc, 0, v117, vcc
	s_waitcnt lgkmcnt(0)
	global_store_dwordx4 v[116:117], v[108:111], off
	s_nop 1

; __device__ __forceinline__ unsigned cvt_pk_bf16(float lo, float hi) { const f32x2_t f = {lo, hi}; const bf16x2_t v = __builtin_convertvector(f, bf16x2_t); return __builtin_bit_cast(unsigned, v); }
; __device__ __forceinline__ u32x4 pack8(const f32x4 a, const f32x4 b) { u32x4 w; w.x = cvt_pk_bf16(a[0], a[1]); w.y = cvt_pk_bf16(a[2], a[3]); w.z = cvt_pk_bf16(b[0], b[1]); w.w = cvt_pk_bf16(b[2], b[3]); return w; }
; __device__ __forceinline__ void store_T8(bf16_t* p, const f32x4 a, const f32x4 b, const int odd) {
;     bf16_t* q = odd ? p + 4 * (size_t)SEQ - 1 : p;
; #pragma unroll
;     for (int j = 0; j < 4; ++j) {
;         const float pa = __shfl_xor(a[j], 1), pb = __shfl_xor(b[j], 1);
;         *(unsigned*)(q + (size_t)j * SEQ) = odd ? cvt_pk_bf16(pb, b[j]) : cvt_pk_bf16(a[j], pa);
;     }
; }
;     __device__ __forceinline__ void operator()(const f32x4 (&acc)[2][2][4][2], const Unit& u, int wr, int wc, int fr_, int fq_) const {
;     ...
;                 for (int bj = 0; bj < 2; ++bj) {
;                     const f32x4 v0 = (acc[ai][bj][m][0] - mu * c1v[bj][0]) * rs + c2v[bj][0];
;                     const f32x4 v1 = (acc[ai][bj][m][1] - mu * c1v[bj][1]) * rs + c2v[bj][1];
;                     const int col = bj * 128 + lc;
;                     if (pn == 12) { if (col < 32) { *(f32x4*)(LR + (size_t)grow * 32 + col) = v0; *(f32x4*)(LR + (size_t)grow * 32 + col + 4) = v1; } }
;                     else {
;                         if (isP) *(u32x4*)(P + (size_t)grow * 2048 + pcol0 + col) = pack8(v0, v1);
;                         if (isT) store_T8(tb[bj] + tok, v0, v1, fr & 1);
;                     }
.LBB0_308:
	s_andn2_b64 vcc, exec, s[60:61]
	s_cbranch_vccnz .LBB0_310
	v_mov_b32_dpp v104, v100 quad_perm:[1,0,3,2] row_mask:0xf bank_mask:0xf
	v_mov_b32_dpp v106, v96 quad_perm:[1,0,3,2] row_mask:0xf bank_mask:0xf
	v_cndmask_b32_e64 v100, v106, v100, s[42:43]
	v_cndmask_b32_e64 v96, v96, v104, s[42:43]
	v_cvt_pk_bf16_f32 v100, v100, v96
	v_mov_b32_dpp v104, v101 quad_perm:[1,0,3,2] row_mask:0xf bank_mask:0xf
	v_mov_b32_dpp v106, v97 quad_perm:[1,0,3,2] row_mask:0xf bank_mask:0xf
	v_cndmask_b32_e64 v101, v106, v101, s[42:43]
	v_cndmask_b32_e64 v97, v97, v104, s[42:43]
	v_cvt_pk_bf16_f32 v101, v101, v97
	v_mov_b32_dpp v104, v102 quad_perm:[1,0,3,2] row_mask:0xf bank_mask:0xf
	v_mov_b32_dpp v106, v98 quad_perm:[1,0,3,2] row_mask:0xf bank_mask:0xf
	v_cndmask_b32_e64 v102, v106, v102, s[42:43]
	v_cndmask_b32_e64 v98, v98, v104, s[42:43]
	v_cvt_pk_bf16_f32 v102, v102, v98
	v_mov_b32_dpp v104, v103 quad_perm:[1,0,3,2] row_mask:0xf bank_mask:0xf
	v_mov_b32_dpp v106, v99 quad_perm:[1,0,3,2] row_mask:0xf bank_mask:0xf
	v_cndmask_b32_e64 v103, v106, v103, s[42:43]
	v_cndmask_b32_e64 v99, v99, v104, s[42:43]
	v_cvt_pk_bf16_f32 v103, v103, v99
	v_lshrrev_b32_e32 v104, 6, v250
	v_mul_u32_u24_e32 v104, 0xc00, v104
	v_and_b32_e32 v106, 48, v231
	v_lshl_add_u32 v104, v106, 4, v104
	v_add_u32_e32 v104, 0x20400, v104
	v_and_b32_e32 v106, 1, v231
	v_lshl_add_u32 v105, v106, 7, v104
	v_and_b32_e32 v106, 14, v231
	v_lshl_add_u32 v105, v106, 1, v105
	v_add_u32_e32 v105, 2048, v105
	ds_write_b32 v105, v100 offset:0
	ds_write_b32 v105, v101 offset:32
	ds_write_b32 v105, v102 offset:64
	ds_write_b32 v105, v103 offset:96
	v_and_b32_e32 v106, 15, v231
	v_lshrrev_b32_e32 v105, 2, v106
	v_lshl_add_u32 v104, v105, 5, v104
	v_and_b32_e32 v105, 1, v106
	v_lshl_add_u32 v104, v105, 4, v104
	v_bfe_u32 v105, v106, 1, 1
	v_mul_u32_u24_e32 v105, 1024, v105
	v_add_u32_e32 v104, v104, v105
	v_add_u32_e32 v104, 1024, v104
	v_and_b32_e32 v108, 3, v106
	v_lshlrev_b32_e32 v108, 3, v108
	v_sub_u32_e32 v108, v108, v106
	v_add_u32_e32 v108, -16, v108
	v_lshlrev_b32_e32 v108, 1, v108
	v_lshrrev_b32_e32 v106, 2, v106
	v_lshl_add_u32 v105, v106, 12, v108
	v_ashrrev_i32_e32 v108, 31, v105
	v_lshl_add_u64 v[38:39], v[38:39], 1, v[58:59]
	v_add_co_u32_e32 v38, vcc, v105, v38
	s_nop 1
	v_addc_co_u32_e32 v39, vcc, v108, v39, vcc
	s_waitcnt lgkmcnt(0)
	ds_read_b128 v[96:99], v104
	ds_read_b128 v[100:103], v104 offset:128
	s_waitcnt lgkmcnt(1)
	global_store_dwordx4 v[38:39], v[96:99], off
	v_add_co_u32_e32 v38, vcc, 0x4000, v38
	s_nop 1
	v_addc_co_u32_e32 v39, vcc, 0, v39, vcc
	s_waitcnt lgkmcnt(0)
	global_store_dwordx4 v[38:39], v[100:103], off
	s_nop 1

; __device__ __forceinline__ unsigned cvt_pk_bf16(float lo, float hi) { const f32x2_t f = {lo, hi}; const bf16x2_t v = __builtin_convertvector(f, bf16x2_t); return __builtin_bit_cast(unsigned, v); }
; __device__ __forceinline__ u32x4 pack8(const f32x4 a, const f32x4 b) { u32x4 w; w.x = cvt_pk_bf16(a[0], a[1]); w.y = cvt_pk_bf16(a[2], a[3]); w.z = cvt_pk_bf16(b[0], b[1]); w.w = cvt_pk_bf16(b[2], b[3]); return w; }
; __device__ __forceinline__ void store_T8(bf16_t* p, const f32x4 a, const f32x4 b, const int odd) {
;     bf16_t* q = odd ? p + 4 * (size_t)SEQ - 1 : p;
; #pragma unroll
;     for (int j = 0; j < 4; ++j) {
;         const float pa = __shfl_xor(a[j], 1), pb = __shfl_xor(b[j], 1);
;         *(unsigned*)(q + (size_t)j * SEQ) = odd ? cvt_pk_bf16(pb, b[j]) : cvt_pk_bf16(a[j], pa);
;     }
; }
;     __device__ __forceinline__ void operator()(const f32x4 (&acc)[2][2][4][2], const Unit& u, int wr, int wc, int fr_, int fq_) const {
;     ...
;                 for (int bj = 0; bj < 2; ++bj) {
;                     const f32x4 v0 = (acc[ai][bj][m][0] - mu * c1v[bj][0]) * rs + c2v[bj][0];
;                     const f32x4 v1 = (acc[ai][bj][m][1] - mu * c1v[bj][1]) * rs + c2v[bj][1];
;                     const int col = bj * 128 + lc;
;                     if (pn == 12) { if (col < 32) { *(f32x4*)(LR + (size_t)grow * 32 + col) = v0; *(f32x4*)(LR + (size_t)grow * 32 + col + 4) = v1; } }
;                     else {
;                         if (isP) *(u32x4*)(P + (size_t)grow * 2048 + pcol0 + col) = pack8(v0, v1);
;                         if (isT) store_T8(tb[bj] + tok, v0, v1, fr & 1);
;                     }
.LBB0_327:
	s_andn2_b64 vcc, exec, s[60:61]
	s_cbranch_vccnz .LBB0_329
	v_mov_b32_dpp v97, v92 quad_perm:[1,0,3,2] row_mask:0xf bank_mask:0xf
	v_mov_b32_dpp v100, v88 quad_perm:[1,0,3,2] row_mask:0xf bank_mask:0xf
	v_cndmask_b32_e64 v92, v100, v92, s[42:43]
	v_cndmask_b32_e64 v88, v88, v97, s[42:43]
	v_cvt_pk_bf16_f32 v92, v92, v88
	v_mov_b32_dpp v97, v93 quad_perm:[1,0,3,2] row_mask:0xf bank_mask:0xf
	v_mov_b32_dpp v100, v89 quad_perm:[1,0,3,2] row_mask:0xf bank_mask:0xf
	v_cndmask_b32_e64 v93, v100, v93, s[42:43]
	v_cndmask_b32_e64 v89, v89, v97, s[42:43]
	v_cvt_pk_bf16_f32 v93, v93, v89
	v_mov_b32_dpp v97, v94 quad_perm:[1,0,3,2] row_mask:0xf bank_mask:0xf
	v_mov_b32_dpp v100, v90 quad_perm:[1,0,3,2] row_mask:0xf bank_mask:0xf
	v_cndmask_b32_e64 v94, v100, v94, s[42:43]
	v_cndmask_b32_e64 v90, v90, v97, s[42:43]
	v_cvt_pk_bf16_f32 v94, v94, v90
	v_mov_b32_dpp v97, v95 quad_perm:[1,0,3,2] row_mask:0xf bank_mask:0xf
	v_mov_b32_dpp v100, v91 quad_perm:[1,0,3,2] row_mask:0xf bank_mask:0xf
	v_cndmask_b32_e64 v95, v100, v95, s[42:43]
	v_cndmask_b32_e64 v91, v91, v97, s[42:43]
	v_cvt_pk_bf16_f32 v95, v95, v91
	v_lshrrev_b32_e32 v97, 6, v250
	v_mul_u32_u24_e32 v97, 0xc00, v97
	v_and_b32_e32 v100, 48, v231
	v_lshl_add_u32 v97, v100, 4, v97
	v_add_u32_e32 v97, 0x20400, v97
	v_and_b32_e32 v100, 1, v231
	v_lshl_add_u32 v103, v100, 7, v97
	v_and_b32_e32 v100, 14, v231
	v_lshl_add_u32 v103, v100, 1, v103
	ds_write_b32 v103, v92 offset:0
	ds_write_b32 v103, v93 offset:32
	ds_write_b32 v103, v94 offset:64
	ds_write_b32 v103, v95 offset:96

; __device__ __forceinline__ unsigned cvt_pk_bf16(float lo, float hi) { const f32x2_t f = {lo, hi}; const bf16x2_t v = __builtin_convertvector(f, bf16x2_t); return __builtin_bit_cast(unsigned, v); }
; __device__ __forceinline__ u32x4 pack8(const f32x4 a, const f32x4 b) { u32x4 w; w.x = cvt_pk_bf16(a[0], a[1]); w.y = cvt_pk_bf16(a[2], a[3]); w.z = cvt_pk_bf16(b[0], b[1]); w.w = cvt_pk_bf16(b[2], b[3]); return w; }
; __device__ __forceinline__ void store_T8(bf16_t* p, const f32x4 a, const f32x4 b, const int odd) {
;     bf16_t* q = odd ? p + 4 * (size_t)SEQ - 1 : p;
; #pragma unroll
;     for (int j = 0; j < 4; ++j) {
;         const float pa = __shfl_xor(a[j], 1), pb = __shfl_xor(b[j], 1);
;         *(unsigned*)(q + (size_t)j * SEQ) = odd ? cvt_pk_bf16(pb, b[j]) : cvt_pk_bf16(a[j], pa);
;     }
; }
;     __device__ __forceinline__ void operator()(const f32x4 (&acc)[2][2][4][2], const Unit& u, int wr, int wc, int fr_, int fq_) const {
;     ...
;                 for (int bj = 0; bj < 2; ++bj) {
;                     const f32x4 v0 = (acc[ai][bj][m][0] - mu * c1v[bj][0]) * rs + c2v[bj][0];
;                     const f32x4 v1 = (acc[ai][bj][m][1] - mu * c1v[bj][1]) * rs + c2v[bj][1];
;                     const int col = bj * 128 + lc;
;                     if (pn == 12) { if (col < 32) { *(f32x4*)(LR + (size_t)grow * 32 + col) = v0; *(f32x4*)(LR + (size_t)grow * 32 + col + 4) = v1; } }
;                     else {
;                         if (isP) *(u32x4*)(P + (size_t)grow * 2048 + pcol0 + col) = pack8(v0, v1);
;                         if (isT) store_T8(tb[bj] + tok, v0, v1, fr & 1);
;                     }
.LBB0_337:
	s_andn2_b64 vcc, exec, s[60:61]
	s_cbranch_vccnz .LBB0_339
	v_mov_b32_dpp v88, v84 quad_perm:[1,0,3,2] row_mask:0xf bank_mask:0xf
	v_mov_b32_dpp v90, v80 quad_perm:[1,0,3,2] row_mask:0xf bank_mask:0xf
	v_cndmask_b32_e64 v84, v90, v84, s[42:43]
	v_cndmask_b32_e64 v80, v80, v88, s[42:43]
	v_cvt_pk_bf16_f32 v84, v84, v80
	v_mov_b32_dpp v88, v85 quad_perm:[1,0,3,2] row_mask:0xf bank_mask:0xf
	v_mov_b32_dpp v90, v81 quad_perm:[1,0,3,2] row_mask:0xf bank_mask:0xf
	v_cndmask_b32_e64 v85, v90, v85, s[42:43]
	v_cndmask_b32_e64 v81, v81, v88, s[42:43]
	v_cvt_pk_bf16_f32 v85, v85, v81
	v_mov_b32_dpp v88, v86 quad_perm:[1,0,3,2] row_mask:0xf bank_mask:0xf
	v_mov_b32_dpp v90, v82 quad_perm:[1,0,3,2] row_mask:0xf bank_mask:0xf
	v_cndmask_b32_e64 v86, v90, v86, s[42:43]
	v_cndmask_b32_e64 v82, v82, v88, s[42:43]
	v_cvt_pk_bf16_f32 v86, v86, v82
	v_mov_b32_dpp v88, v87 quad_perm:[1,0,3,2] row_mask:0xf bank_mask:0xf
	v_mov_b32_dpp v90, v83 quad_perm:[1,0,3,2] row_mask:0xf bank_mask:0xf
	v_cndmask_b32_e64 v87, v90, v87, s[42:43]
	v_cndmask_b32_e64 v83, v83, v88, s[42:43]
	v_cvt_pk_bf16_f32 v87, v87, v83
	v_lshrrev_b32_e32 v88, 6, v250
	v_mul_u32_u24_e32 v88, 0xc00, v88
	v_and_b32_e32 v90, 48, v231
	v_lshl_add_u32 v88, v90, 4, v88
	v_add_u32_e32 v88, 0x20400, v88
	v_and_b32_e32 v90, 1, v231
	v_lshl_add_u32 v89, v90, 7, v88
	v_and_b32_e32 v90, 14, v231
	v_lshl_add_u32 v89, v90, 1, v89
	v_add_u32_e32 v89, 1024, v89
	ds_write_b32 v89, v84 offset:0
	ds_write_b32 v89, v85 offset:32
	ds_write_b32 v89, v86 offset:64
	ds_write_b32 v89, v87 offset:96

; __device__ __forceinline__ unsigned cvt_pk_bf16(float lo, float hi) { const f32x2_t f = {lo, hi}; const bf16x2_t v = __builtin_convertvector(f, bf16x2_t); return __builtin_bit_cast(unsigned, v); }
; __device__ __forceinline__ u32x4 pack8(const f32x4 a, const f32x4 b) { u32x4 w; w.x = cvt_pk_bf16(a[0], a[1]); w.y = cvt_pk_bf16(a[2], a[3]); w.z = cvt_pk_bf16(b[0], b[1]); w.w = cvt_pk_bf16(b[2], b[3]); return w; }
; __device__ __forceinline__ void store_T8(bf16_t* p, const f32x4 a, const f32x4 b, const int odd) {
;     bf16_t* q = odd ? p + 4 * (size_t)SEQ - 1 : p;
; #pragma unroll
;     for (int j = 0; j < 4; ++j) {
;         const float pa = __shfl_xor(a[j], 1), pb = __shfl_xor(b[j], 1);
;         *(unsigned*)(q + (size_t)j * SEQ) = odd ? cvt_pk_bf16(pb, b[j]) : cvt_pk_bf16(a[j], pa);
;     }
; }
;     __device__ __forceinline__ void operator()(const f32x4 (&acc)[2][2][4][2], const Unit& u, int wr, int wc, int fr_, int fq_) const {
;     ...
;                 for (int bj = 0; bj < 2; ++bj) {
;                     const f32x4 v0 = (acc[ai][bj][m][0] - mu * c1v[bj][0]) * rs + c2v[bj][0];
;                     const f32x4 v1 = (acc[ai][bj][m][1] - mu * c1v[bj][1]) * rs + c2v[bj][1];
;                     const int col = bj * 128 + lc;
;                     if (pn == 12) { if (col < 32) { *(f32x4*)(LR + (size_t)grow * 32 + col) = v0; *(f32x4*)(LR + (size_t)grow * 32 + col + 4) = v1; } }
;                     else {
;                         if (isP) *(u32x4*)(P + (size_t)grow * 2048 + pcol0 + col) = pack8(v0, v1);
;                         if (isT) store_T8(tb[bj] + tok, v0, v1, fr & 1);
;                     }
.LBB0_347:
	s_andn2_b64 vcc, exec, s[60:61]
	s_cbranch_vccnz .LBB0_349
	v_mov_b32_dpp v86, v76 quad_perm:[1,0,3,2] row_mask:0xf bank_mask:0xf
	v_mov_b32_dpp v88, v72 quad_perm:[1,0,3,2] row_mask:0xf bank_mask:0xf
	v_cndmask_b32_e64 v76, v88, v76, s[42:43]
	v_cndmask_b32_e64 v72, v72, v86, s[42:43]
	v_cvt_pk_bf16_f32 v76, v76, v72
	v_mov_b32_dpp v86, v77 quad_perm:[1,0,3,2] row_mask:0xf bank_mask:0xf
	v_mov_b32_dpp v88, v73 quad_perm:[1,0,3,2] row_mask:0xf bank_mask:0xf
	v_cndmask_b32_e64 v77, v88, v77, s[42:43]
	v_cndmask_b32_e64 v73, v73, v86, s[42:43]
	v_cvt_pk_bf16_f32 v77, v77, v73
	v_mov_b32_dpp v86, v78 quad_perm:[1,0,3,2] row_mask:0xf bank_mask:0xf
	v_mov_b32_dpp v88, v74 quad_perm:[1,0,3,2] row_mask:0xf bank_mask:0xf
	v_cndmask_b32_e64 v78, v88, v78, s[42:43]
	v_cndmask_b32_e64 v74, v74, v86, s[42:43]
	v_cvt_pk_bf16_f32 v78, v78, v74
	v_mov_b32_dpp v86, v79 quad_perm:[1,0,3,2] row_mask:0xf bank_mask:0xf
	v_mov_b32_dpp v88, v75 quad_perm:[1,0,3,2] row_mask:0xf bank_mask:0xf
	v_cndmask_b32_e64 v79, v88, v79, s[42:43]
	v_cndmask_b32_e64 v75, v75, v86, s[42:43]
	v_cvt_pk_bf16_f32 v79, v79, v75
	v_lshrrev_b32_e32 v86, 6, v250
	v_mul_u32_u24_e32 v86, 0xc00, v86
	v_and_b32_e32 v88, 48, v231
	v_lshl_add_u32 v86, v88, 4, v86
	v_add_u32_e32 v86, 0x20400, v86
	v_and_b32_e32 v88, 1, v231
	v_lshl_add_u32 v87, v88, 7, v86
	v_and_b32_e32 v88, 14, v231
	v_lshl_add_u32 v87, v88, 1, v87
	v_add_u32_e32 v87, 2048, v87
	ds_write_b32 v87, v76 offset:0
	ds_write_b32 v87, v77 offset:32
	ds_write_b32 v87, v78 offset:64
	ds_write_b32 v87, v79 offset:96
	v_and_b32_e32 v88, 15, v231
	v_lshrrev_b32_e32 v87, 2, v88
	v_lshl_add_u32 v86, v87, 5, v86
	v_and_b32_e32 v87, 1, v88
	v_lshl_add_u32 v86, v87, 4, v86
	v_bfe_u32 v87, v88, 1, 1
	v_mul_u32_u24_e32 v87, 2048, v87
	v_add_u32_e32 v86, v86, v87
	v_and_b32_e32 v90, 3, v88
	v_lshlrev_b32_e32 v90, 3, v90
	v_sub_u32_e32 v90, v90, v88
	v_add_u32_e32 v90, -16, v90
	v_lshlrev_b32_e32 v90, 1, v90
	v_lshrrev_b32_e32 v88, 2, v88
	v_lshl_add_u32 v87, v88, 12, v90
	v_ashrrev_i32_e32 v90, 31, v87
	v_lshl_add_u64 v[84:85], v[80:81], 1, v[164:165]
	v_add_co_u32_e32 v84, vcc, v87, v84
	s_nop 1
	v_addc_co_u32_e32 v85, vcc, v90, v85, vcc
	s_waitcnt lgkmcnt(0)
	ds_read_b128 v[72:75], v86
	ds_read_b128 v[76:79], v86 offset:128
	s_waitcnt lgkmcnt(1)
	global_store_dwordx4 v[84:85], v[72:75], off
	v_add_co_u32_e32 v84, vcc, 0x4000, v84
	s_nop 1
	v_addc_co_u32_e32 v85, vcc, 0, v85, vcc
	s_waitcnt lgkmcnt(0)
	global_store_dwordx4 v[84:85], v[76:79], off
	s_nop 1

; __device__ __forceinline__ unsigned cvt_pk_bf16(float lo, float hi) { const f32x2_t f = {lo, hi}; const bf16x2_t v = __builtin_convertvector(f, bf16x2_t); return __builtin_bit_cast(unsigned, v); }
; __device__ __forceinline__ u32x4 pack8(const f32x4 a, const f32x4 b) { u32x4 w; w.x = cvt_pk_bf16(a[0], a[1]); w.y = cvt_pk_bf16(a[2], a[3]); w.z = cvt_pk_bf16(b[0], b[1]); w.w = cvt_pk_bf16(b[2], b[3]); return w; }
; __device__ __forceinline__ void store_T8(bf16_t* p, const f32x4 a, const f32x4 b, const int odd) {
;     bf16_t* q = odd ? p + 4 * (size_t)SEQ - 1 : p;
; #pragma unroll
;     for (int j = 0; j < 4; ++j) {
;         const float pa = __shfl_xor(a[j], 1), pb = __shfl_xor(b[j], 1);
;         *(unsigned*)(q + (size_t)j * SEQ) = odd ? cvt_pk_bf16(pb, b[j]) : cvt_pk_bf16(a[j], pa);
;     }
; }
;     __device__ __forceinline__ void operator()(const f32x4 (&acc)[2][2][4][2], const Unit& u, int wr, int wc, int fr_, int fq_) const {
;     ...
;                         if (isP) *(u32x4*)(P + (size_t)grow * 2048 + pcol0 + col) = pack8(v0, v1);
;                         if (isT) store_T8(tb[bj] + tok, v0, v1, fr & 1);
.LBB0_357:
	s_andn2_b64 vcc, exec, s[60:61]
	s_cbranch_vccnz .LBB0_359
	v_mov_b32_dpp v72, v38 quad_perm:[1,0,3,2] row_mask:0xf bank_mask:0xf
	v_mov_b32_dpp v74, v32 quad_perm:[1,0,3,2] row_mask:0xf bank_mask:0xf
	v_cndmask_b32_e64 v38, v74, v38, s[42:43]
	v_cndmask_b32_e64 v32, v32, v72, s[42:43]
	v_cvt_pk_bf16_f32 v38, v38, v32
	v_mov_b32_dpp v72, v39 quad_perm:[1,0,3,2] row_mask:0xf bank_mask:0xf
	v_mov_b32_dpp v74, v33 quad_perm:[1,0,3,2] row_mask:0xf bank_mask:0xf
	v_cndmask_b32_e64 v39, v74, v39, s[42:43]
	v_cndmask_b32_e64 v33, v33, v72, s[42:43]
	v_cvt_pk_bf16_f32 v39, v39, v33
	v_mov_b32_dpp v72, v40 quad_perm:[1,0,3,2] row_mask:0xf bank_mask:0xf
	v_mov_b32_dpp v74, v34 quad_perm:[1,0,3,2] row_mask:0xf bank_mask:0xf
	v_cndmask_b32_e64 v40, v74, v40, s[42:43]
	v_cndmask_b32_e64 v34, v34, v72, s[42:43]
	v_cvt_pk_bf16_f32 v40, v40, v34
	v_mov_b32_dpp v72, v41 quad_perm:[1,0,3,2] row_mask:0xf bank_mask:0xf
	v_mov_b32_dpp v74, v35 quad_perm:[1,0,3,2] row_mask:0xf bank_mask:0xf
	v_cndmask_b32_e64 v41, v74, v41, s[42:43]
	v_cndmask_b32_e64 v35, v35, v72, s[42:43]
	v_cvt_pk_bf16_f32 v41, v41, v35
	v_lshrrev_b32_e32 v72, 6, v250
	v_mul_u32_u24_e32 v72, 0xc00, v72
	v_and_b32_e32 v74, 48, v231
	v_lshl_add_u32 v72, v74, 4, v72
	v_add_u32_e32 v72, 0x20400, v72
	v_and_b32_e32 v74, 1, v231
	v_lshl_add_u32 v73, v74, 7, v72
	v_and_b32_e32 v74, 14, v231
	v_lshl_add_u32 v73, v74, 1, v73
	v_add_u32_e32 v73, 2048, v73
	ds_write_b32 v73, v38 offset:0
	ds_write_b32 v73, v39 offset:32
	ds_write_b32 v73, v40 offset:64
	ds_write_b32 v73, v41 offset:96
	v_and_b32_e32 v74, 15, v231
	v_lshrrev_b32_e32 v73, 2, v74
	v_lshl_add_u32 v72, v73, 5, v72
	v_and_b32_e32 v73, 1, v74
	v_lshl_add_u32 v72, v73, 4, v72
	v_bfe_u32 v73, v74, 1, 1
	v_mul_u32_u24_e32 v73, 1024, v73
	v_add_u32_e32 v72, v72, v73
	v_add_u32_e32 v72, 1024, v72
	v_and_b32_e32 v76, 3, v74
	v_lshlrev_b32_e32 v76, 3, v76
	v_sub_u32_e32 v76, v76, v74
	v_add_u32_e32 v76, -16, v76
	v_lshlrev_b32_e32 v76, 1, v76
	v_lshrrev_b32_e32 v74, 2, v74
	v_lshl_add_u32 v73, v74, 12, v76
	v_ashrrev_i32_e32 v76, 31, v73
	v_lshl_add_u64 v[42:43], v[80:81], 1, v[58:59]
	v_add_co_u32_e32 v42, vcc, v73, v42
	s_nop 1
	v_addc_co_u32_e32 v43, vcc, v76, v43, vcc
	s_waitcnt lgkmcnt(0)
	ds_read_b128 v[32:35], v72
	ds_read_b128 v[38:41], v72 offset:128
	s_waitcnt lgkmcnt(1)
	global_store_dwordx4 v[42:43], v[32:35], off
	v_add_co_u32_e32 v42, vcc, 0x4000, v42
	s_nop 1
	v_addc_co_u32_e32 v43, vcc, 0, v43, vcc
	s_waitcnt lgkmcnt(0)
	global_store_dwordx4 v[42:43], v[38:41], off
	s_nop 1

; __device__ __forceinline__ unsigned cvt_pk_bf16(float lo, float hi) { const f32x2_t f = {lo, hi}; const bf16x2_t v = __builtin_convertvector(f, bf16x2_t); return __builtin_bit_cast(unsigned, v); }
; __device__ __forceinline__ u32x4 pack8(const f32x4 a, const f32x4 b) { u32x4 w; w.x = cvt_pk_bf16(a[0], a[1]); w.y = cvt_pk_bf16(a[2], a[3]); w.z = cvt_pk_bf16(b[0], b[1]); w.w = cvt_pk_bf16(b[2], b[3]); return w; }
; __device__ __forceinline__ void store_T8(bf16_t* p, const f32x4 a, const f32x4 b, const int odd) {
;     bf16_t* q = odd ? p + 4 * (size_t)SEQ - 1 : p;
; #pragma unroll
;     for (int j = 0; j < 4; ++j) {
;         const float pa = __shfl_xor(a[j], 1), pb = __shfl_xor(b[j], 1);
;         *(unsigned*)(q + (size_t)j * SEQ) = odd ? cvt_pk_bf16(pb, b[j]) : cvt_pk_bf16(a[j], pa);
;     }
; }
;     __device__ __forceinline__ void operator()(const f32x4 (&acc)[2][2][4][2], const Unit& u, int wr, int wc, int fr_, int fq_) const {
;     ...
;                         if (isP) *(u32x4*)(P + (size_t)grow * 2048 + pcol0 + col) = pack8(v0, v1);
;                         if (isT) store_T8(tb[bj] + tok, v0, v1, fr & 1);
.LBB0_367:
	s_andn2_b64 vcc, exec, s[60:61]
	s_cbranch_vccnz .LBB0_369
	v_mov_b32_dpp v42, v28 quad_perm:[1,0,3,2] row_mask:0xf bank_mask:0xf
	v_mov_b32_dpp v72, v24 quad_perm:[1,0,3,2] row_mask:0xf bank_mask:0xf
	v_cndmask_b32_e64 v28, v72, v28, s[42:43]
	v_cndmask_b32_e64 v24, v24, v42, s[42:43]
	v_cvt_pk_bf16_f32 v28, v28, v24
	v_mov_b32_dpp v42, v29 quad_perm:[1,0,3,2] row_mask:0xf bank_mask:0xf
	v_mov_b32_dpp v72, v25 quad_perm:[1,0,3,2] row_mask:0xf bank_mask:0xf
	v_cndmask_b32_e64 v29, v72, v29, s[42:43]
	v_cndmask_b32_e64 v25, v25, v42, s[42:43]
	v_cvt_pk_bf16_f32 v29, v29, v25
	v_mov_b32_dpp v42, v30 quad_perm:[1,0,3,2] row_mask:0xf bank_mask:0xf
	v_mov_b32_dpp v72, v26 quad_perm:[1,0,3,2] row_mask:0xf bank_mask:0xf
	v_cndmask_b32_e64 v30, v72, v30, s[42:43]
	v_cndmask_b32_e64 v26, v26, v42, s[42:43]
	v_cvt_pk_bf16_f32 v30, v30, v26
	v_mov_b32_dpp v42, v31 quad_perm:[1,0,3,2] row_mask:0xf bank_mask:0xf
	v_mov_b32_dpp v72, v27 quad_perm:[1,0,3,2] row_mask:0xf bank_mask:0xf
	v_cndmask_b32_e64 v31, v72, v31, s[42:43]
	v_cndmask_b32_e64 v27, v27, v42, s[42:43]
	v_cvt_pk_bf16_f32 v31, v31, v27
	v_lshrrev_b32_e32 v42, 6, v250
	v_mul_u32_u24_e32 v42, 0xc00, v42
	v_and_b32_e32 v72, 48, v231
	v_lshl_add_u32 v42, v72, 4, v42
	v_add_u32_e32 v42, 0x20400, v42
	v_and_b32_e32 v72, 1, v231
	v_lshl_add_u32 v43, v72, 7, v42
	v_and_b32_e32 v72, 14, v231
	v_lshl_add_u32 v43, v72, 1, v43
	ds_write_b32 v43, v28 offset:0
	ds_write_b32 v43, v29 offset:32
	ds_write_b32 v43, v30 offset:64
	ds_write_b32 v43, v31 offset:96

; __device__ __forceinline__ unsigned cvt_pk_bf16(float lo, float hi) { const f32x2_t f = {lo, hi}; const bf16x2_t v = __builtin_convertvector(f, bf16x2_t); return __builtin_bit_cast(unsigned, v); }
; __device__ __forceinline__ u32x4 pack8(const f32x4 a, const f32x4 b) { u32x4 w; w.x = cvt_pk_bf16(a[0], a[1]); w.y = cvt_pk_bf16(a[2], a[3]); w.z = cvt_pk_bf16(b[0], b[1]); w.w = cvt_pk_bf16(b[2], b[3]); return w; }
; __device__ __forceinline__ void store_T8(bf16_t* p, const f32x4 a, const f32x4 b, const int odd) {
;     bf16_t* q = odd ? p + 4 * (size_t)SEQ - 1 : p;
; #pragma unroll
;     for (int j = 0; j < 4; ++j) {
;         const float pa = __shfl_xor(a[j], 1), pb = __shfl_xor(b[j], 1);
;         *(unsigned*)(q + (size_t)j * SEQ) = odd ? cvt_pk_bf16(pb, b[j]) : cvt_pk_bf16(a[j], pa);
;     }
; }
;     __device__ __forceinline__ void operator()(const f32x4 (&acc)[2][2][4][2], const Unit& u, int wr, int wc, int fr_, int fq_) const {
;     ...
;                         if (isP) *(u32x4*)(P + (size_t)grow * 2048 + pcol0 + col) = pack8(v0, v1);
;                         if (isT) store_T8(tb[bj] + tok, v0, v1, fr & 1);
.LBB0_377:
	s_andn2_b64 vcc, exec, s[60:61]
	s_cbranch_vccnz .LBB0_379
	v_mov_b32_dpp v26, v20 quad_perm:[1,0,3,2] row_mask:0xf bank_mask:0xf
	v_mov_b32_dpp v28, v16 quad_perm:[1,0,3,2] row_mask:0xf bank_mask:0xf
	v_cndmask_b32_e64 v20, v28, v20, s[42:43]
	v_cndmask_b32_e64 v16, v16, v26, s[42:43]
	v_cvt_pk_bf16_f32 v20, v20, v16
	v_mov_b32_dpp v26, v21 quad_perm:[1,0,3,2] row_mask:0xf bank_mask:0xf
	v_mov_b32_dpp v28, v17 quad_perm:[1,0,3,2] row_mask:0xf bank_mask:0xf
	v_cndmask_b32_e64 v21, v28, v21, s[42:43]
	v_cndmask_b32_e64 v17, v17, v26, s[42:43]
	v_cvt_pk_bf16_f32 v21, v21, v17
	v_mov_b32_dpp v26, v22 quad_perm:[1,0,3,2] row_mask:0xf bank_mask:0xf
	v_mov_b32_dpp v28, v18 quad_perm:[1,0,3,2] row_mask:0xf bank_mask:0xf
	v_cndmask_b32_e64 v22, v28, v22, s[42:43]
	v_cndmask_b32_e64 v18, v18, v26, s[42:43]
	v_cvt_pk_bf16_f32 v22, v22, v18
	v_mov_b32_dpp v26, v23 quad_perm:[1,0,3,2] row_mask:0xf bank_mask:0xf
	v_mov_b32_dpp v28, v19 quad_perm:[1,0,3,2] row_mask:0xf bank_mask:0xf
	v_cndmask_b32_e64 v23, v28, v23, s[42:43]
	v_cndmask_b32_e64 v19, v19, v26, s[42:43]
	v_cvt_pk_bf16_f32 v23, v23, v19
	v_lshrrev_b32_e32 v26, 6, v250
	v_mul_u32_u24_e32 v26, 0xc00, v26
	v_and_b32_e32 v28, 48, v231
	v_lshl_add_u32 v26, v28, 4, v26
	v_add_u32_e32 v26, 0x20400, v26
	v_and_b32_e32 v28, 1, v231
	v_lshl_add_u32 v27, v28, 7, v26
	v_and_b32_e32 v28, 14, v231
	v_lshl_add_u32 v27, v28, 1, v27
	v_add_u32_e32 v27, 1024, v27
	ds_write_b32 v27, v20 offset:0
	ds_write_b32 v27, v21 offset:32
	ds_write_b32 v27, v22 offset:64
	ds_write_b32 v27, v23 offset:96

; __device__ __forceinline__ unsigned cvt_pk_bf16(float lo, float hi) { const f32x2_t f = {lo, hi}; const bf16x2_t v = __builtin_convertvector(f, bf16x2_t); return __builtin_bit_cast(unsigned, v); }
; __device__ __forceinline__ u32x4 pack8(const f32x4 a, const f32x4 b) { u32x4 w; w.x = cvt_pk_bf16(a[0], a[1]); w.y = cvt_pk_bf16(a[2], a[3]); w.z = cvt_pk_bf16(b[0], b[1]); w.w = cvt_pk_bf16(b[2], b[3]); return w; }
; __device__ __forceinline__ void store_T8(bf16_t* p, const f32x4 a, const f32x4 b, const int odd) {
;     bf16_t* q = odd ? p + 4 * (size_t)SEQ - 1 : p;
; #pragma unroll
;     for (int j = 0; j < 4; ++j) {
;         const float pa = __shfl_xor(a[j], 1), pb = __shfl_xor(b[j], 1);
;         *(unsigned*)(q + (size_t)j * SEQ) = odd ? cvt_pk_bf16(pb, b[j]) : cvt_pk_bf16(a[j], pa);
;     }
; }
;     __device__ __forceinline__ void operator()(const f32x4 (&acc)[2][2][4][2], const Unit& u, int wr, int wc, int fr_, int fq_) const {
;     ...
;                         if (isP) *(u32x4*)(P + (size_t)grow * 2048 + pcol0 + col) = pack8(v0, v1);
;                         if (isT) store_T8(tb[bj] + tok, v0, v1, fr & 1);
.LBB0_387:
	s_andn2_b64 vcc, exec, s[60:61]
	s_cbranch_vccnz .LBB0_389
	v_mov_b32_dpp v24, v12 quad_perm:[1,0,3,2] row_mask:0xf bank_mask:0xf
	v_mov_b32_dpp v26, v8 quad_perm:[1,0,3,2] row_mask:0xf bank_mask:0xf
	v_cndmask_b32_e64 v12, v26, v12, s[42:43]
	v_cndmask_b32_e64 v8, v8, v24, s[42:43]
	v_cvt_pk_bf16_f32 v12, v12, v8
	v_mov_b32_dpp v24, v13 quad_perm:[1,0,3,2] row_mask:0xf bank_mask:0xf
	v_mov_b32_dpp v26, v9 quad_perm:[1,0,3,2] row_mask:0xf bank_mask:0xf
	v_cndmask_b32_e64 v13, v26, v13, s[42:43]
	v_cndmask_b32_e64 v9, v9, v24, s[42:43]
	v_cvt_pk_bf16_f32 v13, v13, v9
	v_mov_b32_dpp v24, v14 quad_perm:[1,0,3,2] row_mask:0xf bank_mask:0xf
	v_mov_b32_dpp v26, v10 quad_perm:[1,0,3,2] row_mask:0xf bank_mask:0xf
	v_cndmask_b32_e64 v14, v26, v14, s[42:43]
	v_cndmask_b32_e64 v10, v10, v24, s[42:43]
	v_cvt_pk_bf16_f32 v14, v14, v10
	v_mov_b32_dpp v24, v15 quad_perm:[1,0,3,2] row_mask:0xf bank_mask:0xf
	v_mov_b32_dpp v26, v11 quad_perm:[1,0,3,2] row_mask:0xf bank_mask:0xf
	v_cndmask_b32_e64 v15, v26, v15, s[42:43]
	v_cndmask_b32_e64 v11, v11, v24, s[42:43]
	v_cvt_pk_bf16_f32 v15, v15, v11
	v_lshrrev_b32_e32 v24, 6, v250
	v_mul_u32_u24_e32 v24, 0xc00, v24
	v_and_b32_e32 v26, 48, v231
	v_lshl_add_u32 v24, v26, 4, v24
	v_add_u32_e32 v24, 0x20400, v24
	v_and_b32_e32 v26, 1, v231
	v_lshl_add_u32 v25, v26, 7, v24
	v_and_b32_e32 v26, 14, v231
	v_lshl_add_u32 v25, v26, 1, v25
	v_add_u32_e32 v25, 2048, v25
	ds_write_b32 v25, v12 offset:0
	ds_write_b32 v25, v13 offset:32
	ds_write_b32 v25, v14 offset:64
	ds_write_b32 v25, v15 offset:96
	v_and_b32_e32 v26, 15, v231
	v_lshrrev_b32_e32 v25, 2, v26
	v_lshl_add_u32 v24, v25, 5, v24
	v_and_b32_e32 v25, 1, v26
	v_lshl_add_u32 v24, v25, 4, v24
	v_bfe_u32 v25, v26, 1, 1
	v_mul_u32_u24_e32 v25, 2048, v25
	v_add_u32_e32 v24, v24, v25
	v_and_b32_e32 v28, 3, v26
	v_lshlrev_b32_e32 v28, 3, v28
	v_sub_u32_e32 v28, v28, v26
	v_add_u32_e32 v28, -16, v28
	v_lshlrev_b32_e32 v28, 1, v28
	v_lshrrev_b32_e32 v26, 2, v26
	v_lshl_add_u32 v25, v26, 12, v28
	v_ashrrev_i32_e32 v28, 31, v25
	v_lshl_add_u64 v[22:23], v[16:17], 1, v[164:165]
	v_add_co_u32_e32 v22, vcc, v25, v22
	s_nop 1
	v_addc_co_u32_e32 v23, vcc, v28, v23, vcc
	s_waitcnt lgkmcnt(0)
	ds_read_b128 v[8:11], v24
	ds_read_b128 v[12:15], v24 offset:128
	s_waitcnt lgkmcnt(1)
	global_store_dwordx4 v[22:23], v[8:11], off
	v_add_co_u32_e32 v22, vcc, 0x4000, v22
	s_nop 1
	v_addc_co_u32_e32 v23, vcc, 0, v23, vcc
	s_waitcnt lgkmcnt(0)
	global_store_dwordx4 v[22:23], v[12:15], off
	s_nop 1

; __device__ __forceinline__ unsigned cvt_pk_bf16(float lo, float hi) { const f32x2_t f = {lo, hi}; const bf16x2_t v = __builtin_convertvector(f, bf16x2_t); return __builtin_bit_cast(unsigned, v); }
; __device__ __forceinline__ u32x4 pack8(const f32x4 a, const f32x4 b) { u32x4 w; w.x = cvt_pk_bf16(a[0], a[1]); w.y = cvt_pk_bf16(a[2], a[3]); w.z = cvt_pk_bf16(b[0], b[1]); w.w = cvt_pk_bf16(b[2], b[3]); return w; }
; __device__ __forceinline__ void store_T8(bf16_t* p, const f32x4 a, const f32x4 b, const int odd) {
;     bf16_t* q = odd ? p + 4 * (size_t)SEQ - 1 : p;
; #pragma unroll
;     for (int j = 0; j < 4; ++j) {
;         const float pa = __shfl_xor(a[j], 1), pb = __shfl_xor(b[j], 1);
;         *(unsigned*)(q + (size_t)j * SEQ) = odd ? cvt_pk_bf16(pb, b[j]) : cvt_pk_bf16(a[j], pa);
;     }
; }
;     __device__ __forceinline__ void operator()(const f32x4 (&acc)[2][2][4][2], const Unit& u, int wr, int wc, int fr_, int fq_) const {
;     ...
;                         if (isP) *(u32x4*)(P + (size_t)grow * 2048 + pcol0 + col) = pack8(v0, v1);
;                         if (isT) store_T8(tb[bj] + tok, v0, v1, fr & 1);
.LBB0_397:
	s_andn2_b64 vcc, exec, s[60:61]
	s_cbranch_vccnz .LBB0_399
	v_mov_b32_dpp v10, v4 quad_perm:[1,0,3,2] row_mask:0xf bank_mask:0xf
	v_mov_b32_dpp v12, v0 quad_perm:[1,0,3,2] row_mask:0xf bank_mask:0xf
	v_cndmask_b32_e64 v4, v12, v4, s[42:43]
	v_cndmask_b32_e64 v0, v0, v10, s[42:43]
	v_cvt_pk_bf16_f32 v4, v4, v0
	v_mov_b32_dpp v10, v5 quad_perm:[1,0,3,2] row_mask:0xf bank_mask:0xf
	v_mov_b32_dpp v12, v1 quad_perm:[1,0,3,2] row_mask:0xf bank_mask:0xf
	v_cndmask_b32_e64 v5, v12, v5, s[42:43]
	v_cndmask_b32_e64 v1, v1, v10, s[42:43]
	v_cvt_pk_bf16_f32 v5, v5, v1
	v_mov_b32_dpp v10, v6 quad_perm:[1,0,3,2] row_mask:0xf bank_mask:0xf
	v_mov_b32_dpp v12, v2 quad_perm:[1,0,3,2] row_mask:0xf bank_mask:0xf
	v_cndmask_b32_e64 v6, v12, v6, s[42:43]
	v_cndmask_b32_e64 v2, v2, v10, s[42:43]
	v_cvt_pk_bf16_f32 v6, v6, v2
	v_mov_b32_dpp v10, v7 quad_perm:[1,0,3,2] row_mask:0xf bank_mask:0xf
	v_mov_b32_dpp v12, v3 quad_perm:[1,0,3,2] row_mask:0xf bank_mask:0xf
	v_cndmask_b32_e64 v7, v12, v7, s[42:43]
	v_cndmask_b32_e64 v3, v3, v10, s[42:43]
	v_cvt_pk_bf16_f32 v7, v7, v3
	v_lshrrev_b32_e32 v10, 6, v250
	v_mul_u32_u24_e32 v10, 0xc00, v10
	v_and_b32_e32 v12, 48, v231
	v_lshl_add_u32 v10, v12, 4, v10
	v_add_u32_e32 v10, 0x20400, v10
	v_and_b32_e32 v12, 1, v231
	v_lshl_add_u32 v11, v12, 7, v10
	v_and_b32_e32 v12, 14, v231
	v_lshl_add_u32 v11, v12, 1, v11
	v_add_u32_e32 v11, 2048, v11
	ds_write_b32 v11, v4 offset:0
	ds_write_b32 v11, v5 offset:32
	ds_write_b32 v11, v6 offset:64
	ds_write_b32 v11, v7 offset:96
	v_and_b32_e32 v12, 15, v231
	v_lshrrev_b32_e32 v11, 2, v12
	v_lshl_add_u32 v10, v11, 5, v10
	v_and_b32_e32 v11, 1, v12
	v_lshl_add_u32 v10, v11, 4, v10
	v_bfe_u32 v11, v12, 1, 1
	v_mul_u32_u24_e32 v11, 1024, v11
	v_add_u32_e32 v10, v10, v11
	v_add_u32_e32 v10, 1024, v10
	v_and_b32_e32 v14, 3, v12
	v_lshlrev_b32_e32 v14, 3, v14
	v_sub_u32_e32 v14, v14, v12
	v_add_u32_e32 v14, -16, v14
	v_lshlrev_b32_e32 v14, 1, v14
	v_lshrrev_b32_e32 v12, 2, v12
	v_lshl_add_u32 v11, v12, 12, v14
	v_ashrrev_i32_e32 v14, 31, v11
	v_lshl_add_u64 v[8:9], v[16:17], 1, v[58:59]
	v_add_co_u32_e32 v8, vcc, v11, v8
	s_nop 1
	v_addc_co_u32_e32 v9, vcc, v14, v9, vcc
	s_waitcnt lgkmcnt(0)
	ds_read_b128 v[0:3], v10
	ds_read_b128 v[4:7], v10 offset:128
	s_waitcnt lgkmcnt(1)
	global_store_dwordx4 v[8:9], v[0:3], off
	v_add_co_u32_e32 v8, vcc, 0x4000, v8
	s_nop 1
	v_addc_co_u32_e32 v9, vcc, 0, v9, vcc
	s_waitcnt lgkmcnt(0)
	global_store_dwordx4 v[8:9], v[4:7], off
	s_nop 1

; #define LAS __attribute__((address_space(3)))
; __device__ __forceinline__ void nat_dma_k(LAS unsigned char* lds, const bf16_t* P, int wv, int lane, size_t brow, int h, int RB) {
; #pragma unroll
;     for (int q9 = 0; q9 < 9; ++q9) { const int q = wv + 8 * q9, C = 64 * q + lane, key = C >> 3, slot = C & 7, src = slot ^ ((key ^ (key >> 3)) & 7);
;         const int row = min(RB + (key >> 6), 31), tok = row * 64 + (key & 63);
;         __builtin_amdgcn_global_load_lds((const unsigned*)(P + (brow + tok) * 2048 + 1536 + h * 64 + src * 8), (LAS unsigned*)(lds + q * 1024), 16, 0, 0); }
; }
; __device__ __forceinline__ void nat_mfma(LAS unsigned char* lds, const bf16_t* P, const bf16_t* VBT, const float* rpb, bf16_t* MIX) {
;     ...
;         if (k + kstep < kend) { const int k2 = k + kstep, bh2 = xcd_map ? (k2 >> 4) * 8 + (int)(blockIdx.x & 7) : (k2 >> 4), rp2 = k2 & 15;
;             nat_dma_k(lds, P, wv, lane, (size_t)(bh2 >> 3) * SEQ, bh2 & 7, min(max(2 * rp2 - 4, 0), 24)); }
.LBB0_483:
	s_andn2_b64 vcc, exec, s[10:11]
	s_lshl_b32 s86, s86, 6
	s_cbranch_vccnz .LBB0_468
	s_ashr_i32 s2, s79, 1
	s_and_b32 s2, s2, -8
	v_readlane_b32 s4, v252, 51
	s_or_b32 s2, s2, s4
	v_readlane_b32 s4, v252, 53
	s_ashr_i32 s87, s79, 4
	v_readlane_b32 s5, v252, 54
	s_and_b64 s[10:11], s[4:5], exec
	v_readlane_b32 s4, v254, 16
	s_cselect_b32 s2, s2, s87
	s_add_i32 s87, s4, s84
	s_and_b32 s84, s87, 30
	v_sub_u32_e64 v58, s84, 4 clamp
	s_ashr_i32 s10, s2, 3
	v_readfirstlane_b32 s84, v58
	s_min_u32 s84, s84, 24
	s_and_b32 s98, s87, 30
	s_add_i32 s98, s98, s77
	s_lshl_b32 s98, s98, 6
	s_lshl_b32 s99, s10, 11
	s_add_i32 s98, s98, s99
	v_or_b32_e32 v220, s98, v64
	v_mov_b32_e32 v221, 0
	v_lshlrev_b64 v[220:221], 12, v[220:221]
	s_and_b32 s98, s2, 7
	s_lshl_b32 s98, s98, 7
	s_addk_i32 s98, 0x800
	s_mov_b32 s99, 0
	v_lshl_add_u64 v[220:221], s[24:25], 0, v[220:221]
	s_mov_b32 m0, 0x27e20
	v_lshl_add_u64 v[220:221], v[220:221], 0, s[98:99]
	global_load_lds_dword v[220:221], off
	s_add_i32 s88, s84, s90
	s_min_i32 s88, s88, 31
	s_ashr_i32 s11, s10, 31
	v_lshl_or_b32 v148, s88, 6, v128
	s_lshl_b64 s[10:11], s[10:11], 11
	v_ashrrev_i32_e32 v149, 31, v148
	v_lshl_add_u64 v[148:149], s[10:11], 0, v[148:149]
	v_lshlrev_b64 v[148:149], 12, v[148:149]
	s_lshl_b32 s2, s2, 7
	v_lshl_add_u64 v[148:149], s[24:25], 0, v[148:149]
	s_and_b32 s2, s2, 0x380
	v_lshl_add_u64 v[148:149], v[148:149], 0, s[2:3]
	v_mov_b32_e32 v107, v191
	v_lshl_add_u64 v[148:149], v[148:149], 0, v[106:107]
	s_mov_b64 s[4:5], 0xc00
	s_add_i32 s88, s84, s91
	s_mov_b32 m0, s82
	v_lshl_add_u64 v[148:149], v[148:149], 0, s[4:5]
	s_min_i32 s88, s88, 31
	global_load_lds_dwordx4 v[148:149], off
	v_lshl_or_b32 v148, s88, 6, v129
	v_ashrrev_i32_e32 v149, 31, v148
	v_lshl_add_u64 v[148:149], s[10:11], 0, v[148:149]
	v_lshlrev_b64 v[148:149], 12, v[148:149]
	v_lshl_add_u64 v[148:149], s[24:25], 0, v[148:149]
	v_lshl_add_u64 v[148:149], v[148:149], 0, s[2:3]
	v_mov_b32_e32 v109, v191
	v_lshl_add_u64 v[148:149], v[148:149], 0, v[108:109]
	s_add_i32 s88, s84, s97
	v_lshl_add_u64 v[148:149], v[148:149], 0, s[4:5]
	s_mov_b32 m0, s83
	s_min_i32 s88, s88, 31
	global_load_lds_dwordx4 v[148:149], off
	v_lshl_or_b32 v148, s88, 6, v130
	v_ashrrev_i32_e32 v149, 31, v148
	v_lshl_add_u64 v[148:149], s[10:11], 0, v[148:149]
	v_lshlrev_b64 v[148:149], 12, v[148:149]
	v_lshl_add_u64 v[148:149], s[24:25], 0, v[148:149]
	v_lshl_add_u64 v[148:149], v[148:149], 0, s[2:3]
	v_mov_b32_e32 v111, v191
	v_lshl_add_u64 v[148:149], v[148:149], 0, v[110:111]
	s_add_i32 s88, s84, s20
	v_lshl_add_u64 v[148:149], v[148:149], 0, s[4:5]
	s_mov_b32 m0, s23
	s_min_i32 s88, s88, 31
	global_load_lds_dwordx4 v[148:149], off
	v_lshl_or_b32 v148, s88, 6, v131
	v_ashrrev_i32_e32 v149, 31, v148
	v_lshl_add_u64 v[148:149], s[10:11], 0, v[148:149]
	v_lshlrev_b64 v[148:149], 12, v[148:149]
	v_lshl_add_u64 v[148:149], s[24:25], 0, v[148:149]
	v_lshl_add_u64 v[148:149], v[148:149], 0, s[2:3]
	v_mov_b32_e32 v113, v191
	v_lshl_add_u64 v[148:149], v[148:149], 0, v[112:113]
	s_add_i32 s88, s84, s70
	v_lshl_add_u64 v[148:149], v[148:149], 0, s[4:5]
	s_mov_b32 m0, s21
	s_min_i32 s88, s88, 31
	global_load_lds_dwordx4 v[148:149], off
	v_lshl_or_b32 v148, s88, 6, v132
	v_ashrrev_i32_e32 v149, 31, v148
	v_lshl_add_u64 v[148:149], s[10:11], 0, v[148:149]
	v_lshlrev_b64 v[148:149], 12, v[148:149]
	v_lshl_add_u64 v[148:149], s[24:25], 0, v[148:149]
	v_lshl_add_u64 v[148:149], v[148:149], 0, s[2:3]
	v_mov_b32_e32 v115, v191
	v_lshl_add_u64 v[148:149], v[148:149], 0, v[114:115]
	s_add_i32 s88, s84, s72
	v_lshl_add_u64 v[148:149], v[148:149], 0, s[4:5]
	s_mov_b32 m0, s71
	s_min_i32 s88, s88, 31
	global_load_lds_dwordx4 v[148:149], off
	v_lshl_or_b32 v148, s88, 6, v133
	v_ashrrev_i32_e32 v149, 31, v148
	v_lshl_add_u64 v[148:149], s[10:11], 0, v[148:149]
	v_lshlrev_b64 v[148:149], 12, v[148:149]
	v_lshl_add_u64 v[148:149], s[24:25], 0, v[148:149]
	v_lshl_add_u64 v[148:149], v[148:149], 0, s[2:3]
	v_mov_b32_e32 v117, v191
	v_lshl_add_u64 v[148:149], v[148:149], 0, v[116:117]
	s_add_i32 s88, s84, s80
	v_lshl_add_u64 v[148:149], v[148:149], 0, s[4:5]
	s_mov_b32 m0, s73
	s_min_i32 s88, s88, 31
	global_load_lds_dwordx4 v[148:149], off
	v_lshl_or_b32 v148, s88, 6, v134
	v_ashrrev_i32_e32 v149, 31, v148
	v_lshl_add_u64 v[148:149], s[10:11], 0, v[148:149]
	v_lshlrev_b64 v[148:149], 12, v[148:149]
	v_lshl_add_u64 v[148:149], s[24:25], 0, v[148:149]
	v_lshl_add_u64 v[148:149], v[148:149], 0, s[2:3]
	v_mov_b32_e32 v119, v191
	v_lshl_add_u64 v[148:149], v[148:149], 0, v[118:119]
	s_add_i32 s88, s84, s94
	v_lshl_add_u64 v[148:149], v[148:149], 0, s[4:5]
	s_mov_b32 m0, s81
	s_min_i32 s88, s88, 31
	global_load_lds_dwordx4 v[148:149], off
	v_lshl_or_b32 v148, s88, 6, v135
	v_ashrrev_i32_e32 v149, 31, v148
	v_lshl_add_u64 v[148:149], s[10:11], 0, v[148:149]
	v_lshlrev_b64 v[148:149], 12, v[148:149]
	v_lshl_add_u64 v[148:149], s[24:25], 0, v[148:149]
	v_lshl_add_u64 v[148:149], v[148:149], 0, s[2:3]
	v_mov_b32_e32 v121, v191
	v_lshl_add_u64 v[148:149], v[148:149], 0, v[120:121]
	s_add_i32 s84, s84, s34
	v_lshl_add_u64 v[148:149], v[148:149], 0, s[4:5]
	s_mov_b32 m0, s95
	s_min_i32 s84, s84, 31
	global_load_lds_dwordx4 v[148:149], off
	v_lshl_or_b32 v148, s84, 6, v136
	v_ashrrev_i32_e32 v149, 31, v148
	v_lshl_add_u64 v[148:149], s[10:11], 0, v[148:149]
	v_lshlrev_b64 v[148:149], 12, v[148:149]
	v_lshl_add_u64 v[148:149], s[24:25], 0, v[148:149]
	v_lshl_add_u64 v[148:149], v[148:149], 0, s[2:3]
	v_mov_b32_e32 v123, v191
	v_lshl_add_u64 v[148:149], v[148:149], 0, v[122:123]
	v_lshl_add_u64 v[148:149], v[148:149], 0, s[4:5]
	s_mov_b32 m0, s76
	s_nop 0
	global_load_lds_dwordx4 v[148:149], off
	s_branch .LBB0_468

; #define PG8_STAGE(bufoff, gbase, voff) do { _Pragma("unroll") for (int _i = 0; _i < 2; ++_i) \
;         __builtin_amdgcn_global_load_lds((const unsigned*)((const char*)(gbase) + (voff)[_i]), (LAS unsigned*)(lds + (bufoff) + ldsw + _i * 8192), 16, 0, 0); } while (0)
; #define PG8_LDA(dst, b, h) do { _Pragma("unroll") for (int m = 0; m < 4; ++m) _Pragma("unroll") for (int k = 0; k < 2; ++k) dst[m][k] = *(const LAS bf16x8*)(lds + PG8_SA(b, h) + aoff + m * 2048 + k * 1024); } while (0)
; #define PG8_LDB(dst, b, h) do { _Pragma("unroll") for (int n = 0; n < 2; ++n) _Pragma("unroll") for (int k = 0; k < 2; ++k) dst[n][k] = *(const LAS bf16x8*)(lds + PG8_SB(b, h) + boff + n * 2048 + k * 1024); } while (0)
; #define PG8_MMA(ai, bj, At, Bt) do { __builtin_amdgcn_s_setprio(1); _Pragma("unroll") for (int m = 0; m < 4; ++m) _Pragma("unroll") for (int n = 0; n < 2; ++n) _Pragma("unroll") for (int k = 0; k < 2; ++k) \
;         acc[ai][bj][m][n] = __builtin_amdgcn_mfma_f32_16x16x32_bf16(Bt[n][k], At[m][k], acc[ai][bj][m][n], 0, 0, 0); __builtin_amdgcn_s_setprio(0); } while (0)
; #define PG8_WAIT_V(n) asm volatile("s_waitcnt vmcnt(" #n ")" ::: "memory")
; #define PG8_WAIT_L(n) asm volatile("s_waitcnt lgkmcnt(" #n ")" ::: "memory")
; #define PG8_BAR __builtin_amdgcn_s_barrier()
; #define PG8_SCHED __builtin_amdgcn_sched_barrier(0)
; template <class Epi>
; __device__ __forceinline__ void gemm_phase(LAS unsigned char* lds, const Gemm g, const StaticOrder& S, const Epi& E) {
;     ...
;             PG8_LDB(B0, 0, 0); PG8_SCHED; PG8_LDA(At, 0, 0); PG8_STAGE(PG8_SA(1, 1), a1 + hstep, voffA);
;             PG8_WAIT_L(8); PG8_BAR; PG8_WAIT_L(0); PG8_MMA(0, 0, At, B0); PG8_BAR; PG8_SCHED;
;             PG8_LDB(B1, 0, 1); PG8_STAGE(PG8_SB(0, 0), b2, voffB);
;             PG8_BAR; PG8_WAIT_L(0); PG8_MMA(0, 1, At, B1); PG8_BAR;
;             PG8_LDA(At, 0, 1); PG8_STAGE(PG8_SA(0, 0), a2, voffA);
;             PG8_BAR; PG8_WAIT_L(0); PG8_MMA(1, 0, At, B0); PG8_BAR; PG8_SCHED;
;             PG8_STAGE(PG8_SB(0, 1), b2 + hstep, voffB);
;             PG8_WAIT_V(6); PG8_BAR; PG8_MMA(1, 1, At, B1); PG8_BAR;
.LBB0_878:
	s_add_u32 s14, s10, 0xfffc0080
	s_addc_u32 s15, s11, -1
	s_add_i32 s60, 0, 0x10000
	v_add_u32_e32 v76, s60, v217
	ds_read_b128 v[60:63], v76
	ds_read_b128 v[64:67], v76 offset:1024
	ds_read_b128 v[72:75], v76 offset:2048
	ds_read_b128 v[76:79], v76 offset:3072
	s_cmp_eq_u32 s59, 12
	s_cselect_b32 s17, s39, s15
	s_cselect_b32 s16, s55, s14
	s_cselect_b32 s15, s1, s58
	s_cselect_b32 s14, s56, s57
	v_lshl_add_u64 v[188:189], s[10:11], 0, v[174:175]
	s_add_i32 m0, s26, 0xc000
	ds_read_b128 v[80:83], v223
	ds_read_b128 v[84:87], v223 offset:1024
	ds_read_b128 v[92:95], v223 offset:2048
	ds_read_b128 v[96:99], v223 offset:3072
	ds_read_b128 v[160:163], v223 offset:4096
	ds_read_b128 v[164:167], v223 offset:5120
	ds_read_b128 v[178:181], v223 offset:6144
	ds_read_b128 v[182:185], v223 offset:7168
	global_load_lds_dwordx4 v[188:189], off
	v_lshl_add_u64 v[188:189], s[10:11], 0, v[176:177]
	s_add_i32 m0, s26, 0xe000
	s_nop 0
	global_load_lds_dwordx4 v[188:189], off
	s_waitcnt lgkmcnt(8)
	s_barrier
	s_waitcnt lgkmcnt(0)
	s_setprio 1
	s_waitcnt lgkmcnt(0)
	v_mfma_f32_16x16x32_bf16 v[156:159], v[60:63], v[80:83], v[156:159]
	v_mfma_f32_16x16x32_bf16 v[148:151], v[72:75], v[80:83], v[148:151]
	v_mfma_f32_16x16x32_bf16 v[140:143], v[60:63], v[92:95], v[140:143]
	v_mfma_f32_16x16x32_bf16 v[132:135], v[72:75], v[92:95], v[132:135]
	v_mfma_f32_16x16x32_bf16 v[124:127], v[60:63], v[160:163], v[124:127]
	v_mfma_f32_16x16x32_bf16 v[116:119], v[72:75], v[160:163], v[116:119]
	v_mfma_f32_16x16x32_bf16 v[108:111], v[60:63], v[178:181], v[108:111]
	v_mfma_f32_16x16x32_bf16 v[100:103], v[72:75], v[178:181], v[100:103]
	v_mfma_f32_16x16x32_bf16 v[156:159], v[64:67], v[84:87], v[156:159]
	v_mfma_f32_16x16x32_bf16 v[148:151], v[76:79], v[84:87], v[148:151]
	v_mfma_f32_16x16x32_bf16 v[140:143], v[64:67], v[96:99], v[140:143]
	v_mfma_f32_16x16x32_bf16 v[132:135], v[76:79], v[96:99], v[132:135]
	v_mfma_f32_16x16x32_bf16 v[124:127], v[64:67], v[164:167], v[124:127]
	v_mfma_f32_16x16x32_bf16 v[116:119], v[76:79], v[164:167], v[116:119]
	v_mfma_f32_16x16x32_bf16 v[108:111], v[64:67], v[182:185], v[108:111]
	v_mfma_f32_16x16x32_bf16 v[100:103], v[76:79], v[182:185], v[100:103]
	s_setprio 0
	s_barrier
	s_add_i32 s62, 0, 0x14000
	s_add_i32 s60, s60, s21
	v_add_u32_e32 v186, s62, v217
	v_lshl_add_u64 v[188:189], s[14:15], 0, v[190:191]
	s_mov_b32 m0, s60
	ds_read_b128 v[194:197], v186
	ds_read_b128 v[198:201], v186 offset:1024
	ds_read_b128 v[204:207], v186 offset:2048
	ds_read_b128 v[208:211], v186 offset:3072
	global_load_lds_dwordx4 v[188:189], off
	v_lshl_add_u64 v[224:225], s[14:15], 0, v[168:169]
	s_add_i32 m0, s60, 0x2000
	s_nop 0
	global_load_lds_dwordx4 v[224:225], off
	s_barrier
	s_waitcnt lgkmcnt(0)
	s_setprio 1
	s_waitcnt lgkmcnt(0)
	v_mfma_f32_16x16x32_bf16 v[152:155], v[194:197], v[80:83], v[152:155]
	v_mfma_f32_16x16x32_bf16 v[80:83], v[204:207], v[80:83], v[144:147]
	v_mfma_f32_16x16x32_bf16 v[152:155], v[198:201], v[84:87], v[152:155]
	v_mfma_f32_16x16x32_bf16 v[80:83], v[208:211], v[84:87], v[80:83]
	v_mfma_f32_16x16x32_bf16 v[84:87], v[194:197], v[92:95], v[136:139]
	v_mfma_f32_16x16x32_bf16 v[92:95], v[204:207], v[92:95], v[128:131]
	v_mfma_f32_16x16x32_bf16 v[112:115], v[204:207], v[160:163], v[112:115]
	v_mfma_f32_16x16x32_bf16 v[104:107], v[194:197], v[178:181], v[104:107]
	v_mfma_f32_16x16x32_bf16 v[88:91], v[204:207], v[178:181], v[88:91]
	v_mfma_f32_16x16x32_bf16 v[84:87], v[198:201], v[96:99], v[84:87]
	v_mfma_f32_16x16x32_bf16 v[92:95], v[208:211], v[96:99], v[92:95]
	v_mfma_f32_16x16x32_bf16 v[96:99], v[194:197], v[160:163], v[120:123]
	v_mfma_f32_16x16x32_bf16 v[112:115], v[208:211], v[164:167], v[112:115]
	v_mfma_f32_16x16x32_bf16 v[104:107], v[198:201], v[182:185], v[104:107]
	v_mfma_f32_16x16x32_bf16 v[88:91], v[208:211], v[182:185], v[88:91]
	v_mfma_f32_16x16x32_bf16 v[96:99], v[198:201], v[164:167], v[96:99]
	s_setprio 0
	s_mov_b32 m0, s26
	v_lshl_add_u64 v[226:227], s[16:17], 0, v[172:173]
	s_barrier
	ds_read_b128 v[120:123], v223 offset:16384
	ds_read_b128 v[128:131], v223 offset:17408
	ds_read_b128 v[136:139], v223 offset:18432
	ds_read_b128 v[144:147], v223 offset:19456
	ds_read_b128 v[160:163], v223 offset:20480
	ds_read_b128 v[164:167], v223 offset:21504
	ds_read_b128 v[178:181], v223 offset:22528
	ds_read_b128 v[182:185], v223 offset:23552
	global_load_lds_dwordx4 v[226:227], off
	v_lshl_add_u64 v[240:241], s[16:17], 0, v[170:171]
	s_mov_b32 m0, s27
	s_nop 0
	global_load_lds_dwordx4 v[240:241], off
	s_barrier
	s_waitcnt lgkmcnt(0)
	s_setprio 1
	s_waitcnt lgkmcnt(0)
	v_mfma_f32_16x16x32_bf16 v[68:71], v[60:63], v[120:123], v[68:71]
	v_mfma_f32_16x16x32_bf16 v[52:55], v[72:75], v[120:123], v[52:55]
	v_mfma_f32_16x16x32_bf16 v[44:47], v[60:63], v[136:139], v[44:47]
	v_mfma_f32_16x16x32_bf16 v[36:39], v[72:75], v[136:139], v[36:39]
	v_mfma_f32_16x16x32_bf16 v[28:31], v[60:63], v[160:163], v[28:31]
	v_mfma_f32_16x16x32_bf16 v[20:23], v[72:75], v[160:163], v[20:23]
	v_mfma_f32_16x16x32_bf16 v[12:15], v[60:63], v[178:181], v[12:15]
	v_mfma_f32_16x16x32_bf16 v[4:7], v[72:75], v[178:181], v[4:7]
	v_mfma_f32_16x16x32_bf16 v[68:71], v[64:67], v[128:131], v[68:71]
	v_mfma_f32_16x16x32_bf16 v[52:55], v[76:79], v[128:131], v[52:55]
	v_mfma_f32_16x16x32_bf16 v[44:47], v[64:67], v[144:147], v[44:47]
	v_mfma_f32_16x16x32_bf16 v[36:39], v[76:79], v[144:147], v[36:39]
	v_mfma_f32_16x16x32_bf16 v[28:31], v[64:67], v[164:167], v[28:31]
	v_mfma_f32_16x16x32_bf16 v[20:23], v[76:79], v[164:167], v[20:23]
	v_mfma_f32_16x16x32_bf16 v[12:15], v[64:67], v[182:185], v[12:15]
	v_mfma_f32_16x16x32_bf16 v[4:7], v[76:79], v[182:185], v[4:7]
	s_setprio 0
	s_barrier
; #define PG8_STAGE(bufoff, gbase, voff) do { _Pragma("unroll") for (int _i = 0; _i < 2; ++_i) \
;         __builtin_amdgcn_global_load_lds((const unsigned*)((const char*)(gbase) + (voff)[_i]), (LAS unsigned*)(lds + (bufoff) + ldsw + _i * 8192), 16, 0, 0); } while (0)
; #define PG8_LDA(dst, b, h) do { _Pragma("unroll") for (int m = 0; m < 4; ++m) _Pragma("unroll") for (int k = 0; k < 2; ++k) dst[m][k] = *(const LAS bf16x8*)(lds + PG8_SA(b, h) + aoff + m * 2048 + k * 1024); } while (0)
; #define PG8_LDB(dst, b, h) do { _Pragma("unroll") for (int n = 0; n < 2; ++n) _Pragma("unroll") for (int k = 0; k < 2; ++k) dst[n][k] = *(const LAS bf16x8*)(lds + PG8_SB(b, h) + boff + n * 2048 + k * 1024); } while (0)
; #define PG8_MMA(ai, bj, At, Bt) do { __builtin_amdgcn_s_setprio(1); _Pragma("unroll") for (int m = 0; m < 4; ++m) _Pragma("unroll") for (int n = 0; n < 2; ++n) _Pragma("unroll") for (int k = 0; k < 2; ++k) \
;         acc[ai][bj][m][n] = __builtin_amdgcn_mfma_f32_16x16x32_bf16(Bt[n][k], At[m][k], acc[ai][bj][m][n], 0, 0, 0); __builtin_amdgcn_s_setprio(0); } while (0)
; #define PG8_WAIT_V(n) asm volatile("s_waitcnt vmcnt(" #n ")" ::: "memory")
; #define PG8_WAIT_L(n) asm volatile("s_waitcnt lgkmcnt(" #n ")" ::: "memory")
; #define PG8_BAR __builtin_amdgcn_s_barrier()
; #define PG8_SCHED __builtin_amdgcn_sched_barrier(0)
; template <class Epi>
; __device__ __forceinline__ void gemm_phase(LAS unsigned char* lds, const Gemm g, const StaticOrder& S, const Epi& E) {
;     ...
;             PG8_WAIT_V(6); PG8_BAR; PG8_MMA(1, 1, At, B1); PG8_BAR;
;             PG8_LDB(B0, 1, 0); PG8_SCHED; PG8_LDA(At, 1, 0); PG8_STAGE(PG8_SA(0, 1), a2 + hstep, voffA);
;             PG8_WAIT_L(8); PG8_BAR; PG8_WAIT_L(0); PG8_MMA(0, 0, At, B0); PG8_BAR; PG8_SCHED;
;             PG8_LDB(B1, 1, 1); PG8_STAGE(PG8_SB(1, 0), b3, voffB);
;             PG8_BAR; PG8_WAIT_L(0); PG8_MMA(0, 1, At, B1); PG8_BAR;
;             PG8_LDA(At, 1, 1); PG8_STAGE(PG8_SA(1, 0), a3, voffA);
;             PG8_BAR; PG8_WAIT_L(0); PG8_MMA(1, 0, At, B0); PG8_BAR; PG8_SCHED;
	s_add_u32 s60, s14, 0x40000
	s_addc_u32 s61, s15, 0
	s_add_i32 s62, s62, s21
	v_lshl_add_u64 v[60:61], s[60:61], 0, v[190:191]
	s_mov_b32 m0, s62
	s_nop 0
	global_load_lds_dwordx4 v[60:61], off
	v_lshl_add_u64 v[60:61], s[60:61], 0, v[168:169]
	s_add_i32 m0, s62, 0x2000
	s_nop 0
	global_load_lds_dwordx4 v[60:61], off
	s_waitcnt vmcnt(6)
	s_barrier
	s_setprio 1
	v_mfma_f32_16x16x32_bf16 v[56:59], v[194:197], v[120:123], v[56:59]
	v_mfma_f32_16x16x32_bf16 v[48:51], v[204:207], v[120:123], v[48:51]
	v_mfma_f32_16x16x32_bf16 v[40:43], v[194:197], v[136:139], v[40:43]
	v_mfma_f32_16x16x32_bf16 v[32:35], v[204:207], v[136:139], v[32:35]
	v_mfma_f32_16x16x32_bf16 v[24:27], v[194:197], v[160:163], v[24:27]
	v_mfma_f32_16x16x32_bf16 v[16:19], v[204:207], v[160:163], v[16:19]
	v_mfma_f32_16x16x32_bf16 v[8:11], v[194:197], v[178:181], v[8:11]
	v_mfma_f32_16x16x32_bf16 v[0:3], v[204:207], v[178:181], v[0:3]
	v_mfma_f32_16x16x32_bf16 v[56:59], v[198:201], v[128:131], v[56:59]
	v_mfma_f32_16x16x32_bf16 v[48:51], v[208:211], v[128:131], v[48:51]
	v_mfma_f32_16x16x32_bf16 v[40:43], v[198:201], v[144:147], v[40:43]
	v_mfma_f32_16x16x32_bf16 v[32:35], v[208:211], v[144:147], v[32:35]
	v_mfma_f32_16x16x32_bf16 v[24:27], v[198:201], v[164:167], v[24:27]
	v_mfma_f32_16x16x32_bf16 v[16:19], v[208:211], v[164:167], v[16:19]
	v_mfma_f32_16x16x32_bf16 v[8:11], v[198:201], v[182:185], v[8:11]
	v_mfma_f32_16x16x32_bf16 v[0:3], v[208:211], v[182:185], v[0:3]
	s_setprio 0
	s_add_i32 s60, 0, 0x18000
	v_add_u32_e32 v76, s60, v217
	s_barrier
	ds_read_b128 v[60:63], v76
	ds_read_b128 v[64:67], v76 offset:1024
	ds_read_b128 v[72:75], v76 offset:2048
	ds_read_b128 v[76:79], v76 offset:3072
	s_add_u32 s16, s16, 0x40000
	s_addc_u32 s17, s17, 0
	s_mov_b32 m0, s30
	v_lshl_add_u64 v[136:137], s[16:17], 0, v[172:173]
	ds_read_b128 v[120:123], v223 offset:32768
	ds_read_b128 v[128:131], v223 offset:33792
	ds_read_b128 v[160:163], v223 offset:34816
	ds_read_b128 v[164:167], v223 offset:35840
	ds_read_b128 v[178:181], v223 offset:36864
	ds_read_b128 v[182:185], v223 offset:37888
	ds_read_b128 v[194:197], v223 offset:38912
	ds_read_b128 v[198:201], v223 offset:39936
	global_load_lds_dwordx4 v[136:137], off
	v_lshl_add_u64 v[136:137], s[16:17], 0, v[170:171]
	s_mov_b32 m0, s31
	s_nop 0
	global_load_lds_dwordx4 v[136:137], off
	s_waitcnt lgkmcnt(8)
	s_barrier
	s_waitcnt lgkmcnt(0)
	s_setprio 1
	s_waitcnt lgkmcnt(0)
	v_mfma_f32_16x16x32_bf16 v[136:139], v[60:63], v[120:123], v[156:159]
	v_mfma_f32_16x16x32_bf16 v[156:159], v[64:67], v[128:131], v[136:139]
	v_mfma_f32_16x16x32_bf16 v[136:139], v[72:75], v[120:123], v[148:151]
	v_mfma_f32_16x16x32_bf16 v[148:151], v[76:79], v[128:131], v[136:139]
	v_mfma_f32_16x16x32_bf16 v[136:139], v[60:63], v[160:163], v[140:143]
	v_mfma_f32_16x16x32_bf16 v[132:135], v[72:75], v[160:163], v[132:135]
	v_mfma_f32_16x16x32_bf16 v[124:127], v[60:63], v[178:181], v[124:127]
	v_mfma_f32_16x16x32_bf16 v[116:119], v[72:75], v[178:181], v[116:119]
	v_mfma_f32_16x16x32_bf16 v[108:111], v[60:63], v[194:197], v[108:111]
	v_mfma_f32_16x16x32_bf16 v[100:103], v[72:75], v[194:197], v[100:103]
	v_mfma_f32_16x16x32_bf16 v[140:143], v[64:67], v[164:167], v[136:139]
	v_mfma_f32_16x16x32_bf16 v[132:135], v[76:79], v[164:167], v[132:135]
	v_mfma_f32_16x16x32_bf16 v[124:127], v[64:67], v[182:185], v[124:127]
	v_mfma_f32_16x16x32_bf16 v[116:119], v[76:79], v[182:185], v[116:119]
	v_mfma_f32_16x16x32_bf16 v[108:111], v[64:67], v[198:201], v[108:111]
	v_mfma_f32_16x16x32_bf16 v[100:103], v[76:79], v[198:201], v[100:103]
	s_setprio 0
	s_barrier
	s_add_i32 s16, 0, 0x1c000
	v_add_u32_e32 v136, s16, v217
	s_add_i32 s17, s60, s21
	ds_read_b128 v[204:207], v136
	ds_read_b128 v[208:211], v136 offset:1024
	ds_read_b128 v[212:215], v136 offset:2048
	ds_read_b128 v[218:221], v136 offset:3072
	v_lshl_add_u64 v[136:137], v[188:189], 0, s[28:29]
	s_mov_b32 m0, s17
	s_nop 0
	global_load_lds_dwordx4 v[136:137], off
	v_lshl_add_u64 v[136:137], v[224:225], 0, s[28:29]
	s_add_i32 m0, s17, 0x2000
	s_nop 0
	global_load_lds_dwordx4 v[136:137], off
	s_barrier
	s_waitcnt lgkmcnt(0)
	s_setprio 1
	s_waitcnt lgkmcnt(0)
	v_mfma_f32_16x16x32_bf16 v[80:83], v[212:215], v[120:123], v[80:83]
	v_mfma_f32_16x16x32_bf16 v[136:139], v[204:207], v[120:123], v[152:155]
	v_mfma_f32_16x16x32_bf16 v[144:147], v[218:221], v[128:131], v[80:83]
	v_mfma_f32_16x16x32_bf16 v[80:83], v[204:207], v[160:163], v[84:87]
	v_mfma_f32_16x16x32_bf16 v[152:155], v[208:211], v[128:131], v[136:139]
	v_mfma_f32_16x16x32_bf16 v[136:139], v[208:211], v[164:167], v[80:83]
	v_mfma_f32_16x16x32_bf16 v[80:83], v[212:215], v[160:163], v[92:95]
	v_mfma_f32_16x16x32_bf16 v[128:131], v[218:221], v[164:167], v[80:83]
	v_mfma_f32_16x16x32_bf16 v[80:83], v[204:207], v[178:181], v[96:99]
	v_mfma_f32_16x16x32_bf16 v[120:123], v[208:211], v[182:185], v[80:83]
	v_mfma_f32_16x16x32_bf16 v[80:83], v[212:215], v[178:181], v[112:115]
	v_mfma_f32_16x16x32_bf16 v[112:115], v[218:221], v[182:185], v[80:83]
	v_mfma_f32_16x16x32_bf16 v[80:83], v[204:207], v[194:197], v[104:107]
	v_mfma_f32_16x16x32_bf16 v[104:107], v[208:211], v[198:201], v[80:83]
	v_mfma_f32_16x16x32_bf16 v[80:83], v[212:215], v[194:197], v[88:91]
	v_mfma_f32_16x16x32_bf16 v[88:91], v[218:221], v[198:201], v[80:83]
	s_setprio 0
	s_mov_b32 m0, s51
	v_lshl_add_u64 v[188:189], v[226:227], 0, s[28:29]
	s_barrier
	s_nop 2
	ds_read_b128 v[80:83], v223 offset:49152
	ds_read_b128 v[84:87], v223 offset:50176
	ds_read_b128 v[92:95], v223 offset:51200
	ds_read_b128 v[96:99], v223 offset:52224
	ds_read_b128 v[160:163], v223 offset:53248
	ds_read_b128 v[164:167], v223 offset:54272
	ds_read_b128 v[178:181], v223 offset:55296
	ds_read_b128 v[182:185], v223 offset:56320
	global_load_lds_dwordx4 v[188:189], off
	v_lshl_add_u64 v[188:189], v[240:241], 0, s[28:29]
	s_mov_b32 m0, s52
	s_nop 0
	global_load_lds_dwordx4 v[188:189], off
	s_barrier
; #define PG8_STAGE(bufoff, gbase, voff) do { _Pragma("unroll") for (int _i = 0; _i < 2; ++_i) \
;         __builtin_amdgcn_global_load_lds((const unsigned*)((const char*)(gbase) + (voff)[_i]), (LAS unsigned*)(lds + (bufoff) + ldsw + _i * 8192), 16, 0, 0); } while (0)
; #define PG8_LDA(dst, b, h) do { _Pragma("unroll") for (int m = 0; m < 4; ++m) _Pragma("unroll") for (int k = 0; k < 2; ++k) dst[m][k] = *(const LAS bf16x8*)(lds + PG8_SA(b, h) + aoff + m * 2048 + k * 1024); } while (0)
; #define PG8_MMA(ai, bj, At, Bt) do { __builtin_amdgcn_s_setprio(1); _Pragma("unroll") for (int m = 0; m < 4; ++m) _Pragma("unroll") for (int n = 0; n < 2; ++n) _Pragma("unroll") for (int k = 0; k < 2; ++k) \
;         acc[ai][bj][m][n] = __builtin_amdgcn_mfma_f32_16x16x32_bf16(Bt[n][k], At[m][k], acc[ai][bj][m][n], 0, 0, 0); __builtin_amdgcn_s_setprio(0); } while (0)
; #define PG8_WAIT_V(n) asm volatile("s_waitcnt vmcnt(" #n ")" ::: "memory")
; #define PG8_WAIT_L(n) asm volatile("s_waitcnt lgkmcnt(" #n ")" ::: "memory")
; #define PG8_BAR __builtin_amdgcn_s_barrier()
; #define PG8_SCHED __builtin_amdgcn_sched_barrier(0)
; __device__ __forceinline__ void row_stats(const float* st, int row, int fq, float& mu, float& rs) {
;     const f32x4 a = *(const f32x4*)(st + (size_t)row * 32 + fq * 8), b = *(const f32x4*)(st + (size_t)row * 32 + fq * 8 + 4);
;     float s = (a[0] + a[2]) + (b[0] + b[2]), q = (a[1] + a[3]) + (b[1] + b[3]);
;     s += __shfl_xor(s, 16); s += __shfl_xor(s, 32); q += __shfl_xor(q, 16); q += __shfl_xor(q, 32);
;     mu = s * (1.0f / 1024.0f); const float var = fmaxf(q * (1.0f / 1024.0f) - mu * mu, 0.f); rs = rsqrtf(var + LN_EPS);
; template <class Epi>
; __device__ __forceinline__ void gemm_phase(LAS unsigned char* lds, const Gemm g, const StaticOrder& S, const Epi& E) {
;     ...
;             PG8_BAR; PG8_WAIT_L(0); PG8_MMA(0, 1, At, B1); PG8_BAR;
;             PG8_LDA(At, 1, 1); PG8_STAGE(PG8_SA(1, 0), a3, voffA);
;             PG8_BAR; PG8_WAIT_L(0); PG8_MMA(1, 0, At, B0); PG8_BAR; PG8_SCHED;
;             PG8_STAGE(PG8_SB(1, 1), b3 + hstep, voffB);
;             PG8_WAIT_V(6); PG8_BAR; PG8_MMA(1, 1, At, B1); PG8_BAR;
	s_waitcnt lgkmcnt(0)
	s_setprio 1
	s_waitcnt lgkmcnt(0)
	v_mfma_f32_16x16x32_bf16 v[68:71], v[60:63], v[80:83], v[68:71]
	v_mfma_f32_16x16x32_bf16 v[52:55], v[72:75], v[80:83], v[52:55]
	v_mfma_f32_16x16x32_bf16 v[44:47], v[60:63], v[92:95], v[44:47]
	v_mfma_f32_16x16x32_bf16 v[36:39], v[72:75], v[92:95], v[36:39]
	v_mfma_f32_16x16x32_bf16 v[28:31], v[60:63], v[160:163], v[28:31]
	v_mfma_f32_16x16x32_bf16 v[20:23], v[72:75], v[160:163], v[20:23]
	v_mfma_f32_16x16x32_bf16 v[12:15], v[60:63], v[178:181], v[12:15]
	v_mfma_f32_16x16x32_bf16 v[4:7], v[72:75], v[178:181], v[4:7]
	v_mfma_f32_16x16x32_bf16 v[68:71], v[64:67], v[84:87], v[68:71]
	v_mfma_f32_16x16x32_bf16 v[52:55], v[76:79], v[84:87], v[52:55]
	v_mfma_f32_16x16x32_bf16 v[44:47], v[64:67], v[96:99], v[44:47]
	v_mfma_f32_16x16x32_bf16 v[36:39], v[76:79], v[96:99], v[36:39]
	v_mfma_f32_16x16x32_bf16 v[28:31], v[64:67], v[164:167], v[28:31]
	v_mfma_f32_16x16x32_bf16 v[20:23], v[76:79], v[164:167], v[20:23]
	v_mfma_f32_16x16x32_bf16 v[12:15], v[64:67], v[182:185], v[12:15]
	v_mfma_f32_16x16x32_bf16 v[4:7], v[76:79], v[182:185], v[4:7]
	s_setprio 0
	s_barrier
	s_add_u32 s14, s14, 0x40080
	s_addc_u32 s15, s15, 0
	s_add_i32 s16, s16, s21
	v_lshl_add_u64 v[60:61], s[14:15], 0, v[190:191]
	s_mov_b32 m0, s16
	s_nop 0
	global_load_lds_dwordx4 v[60:61], off
	v_lshl_add_u64 v[60:61], s[14:15], 0, v[168:169]
	s_add_i32 m0, s16, 0x2000
	s_nop 0
	global_load_lds_dwordx4 v[60:61], off
	s_waitcnt vmcnt(6)
	s_barrier
	s_setprio 1
	v_mfma_f32_16x16x32_bf16 v[56:59], v[204:207], v[80:83], v[56:59]
	v_mfma_f32_16x16x32_bf16 v[48:51], v[212:215], v[80:83], v[48:51]
	v_mfma_f32_16x16x32_bf16 v[40:43], v[204:207], v[92:95], v[40:43]
	v_mfma_f32_16x16x32_bf16 v[32:35], v[212:215], v[92:95], v[32:35]
	v_mfma_f32_16x16x32_bf16 v[24:27], v[204:207], v[160:163], v[24:27]
	v_mfma_f32_16x16x32_bf16 v[16:19], v[212:215], v[160:163], v[16:19]
	v_mfma_f32_16x16x32_bf16 v[8:11], v[204:207], v[178:181], v[8:11]
	v_mfma_f32_16x16x32_bf16 v[0:3], v[212:215], v[178:181], v[0:3]
	v_mfma_f32_16x16x32_bf16 v[56:59], v[208:211], v[84:87], v[56:59]
	v_mfma_f32_16x16x32_bf16 v[48:51], v[218:221], v[84:87], v[48:51]
	v_mfma_f32_16x16x32_bf16 v[40:43], v[208:211], v[96:99], v[40:43]
	v_mfma_f32_16x16x32_bf16 v[32:35], v[218:221], v[96:99], v[32:35]
	v_mfma_f32_16x16x32_bf16 v[24:27], v[208:211], v[164:167], v[24:27]
	v_mfma_f32_16x16x32_bf16 v[16:19], v[218:221], v[164:167], v[16:19]
	v_mfma_f32_16x16x32_bf16 v[8:11], v[208:211], v[182:185], v[8:11]
	v_mfma_f32_16x16x32_bf16 v[0:3], v[218:221], v[182:185], v[0:3]
	s_setprio 0
	s_add_i32 s59, s59, 2
	s_add_u32 s10, s10, 0x100
	s_addc_u32 s11, s11, 0
	s_add_u32 s57, s57, 0x100
	s_addc_u32 s58, s58, 0
	s_cmp_gt_u32 s59, 13
	s_barrier
	s_cbranch_scc0 .LBB0_878
	s_lshl_b32 s10, s54, 8
	s_ashr_i32 s11, s10, 31
	s_lshl_b64 s[10:11], s[10:11], 2
	s_add_u32 s14, s2, s10
	s_addc_u32 s15, s46, s11
	v_xor_b32_e32 v162, 16, v231
	s_add_u32 s10, s47, s10
	v_cmp_lt_i32_e32 vcc, v162, v232
	v_mov_b32_e32 v161, v187
	v_mov_b32_e32 v60, v203
	s_addc_u32 s11, s48, s11
	s_lshl_b32 s1, s5, 8
	v_cndmask_b32_e32 v162, v231, v162, vcc
	s_add_i32 s1, s1, s49
	v_lshlrev_b32_e32 v160, 3, v60
	v_lshlrev_b32_e32 v239, 2, v162
	v_xor_b32_e32 v162, 32, v231
	v_add_u32_e32 v188, s50, v160
	v_add_u32_e32 v210, s1, v161
	v_readlane_b32 s4, v253, 21
	v_cmp_lt_i32_e32 vcc, v162, v232
	v_ashrrev_i32_e32 v189, 31, v188
	v_ashrrev_i32_e32 v161, 31, v160
	v_readlane_b32 s5, v253, 22
	v_cndmask_b32_e32 v162, v231, v162, vcc
	v_ashrrev_i32_e32 v211, 31, v210
	v_lshlrev_b64 v[60:61], 2, v[188:189]
	v_lshl_add_u64 v[160:161], v[160:161], 2, s[4:5]
	v_lshlrev_b32_e32 v225, 2, v162
	v_lshlrev_b64 v[162:163], 7, v[210:211]
	v_lshl_add_u64 v[64:65], s[14:15], 0, v[60:61]
	v_lshl_add_u64 v[84:85], s[10:11], 0, v[60:61]
	v_lshl_add_u64 v[166:167], v[160:161], 0, v[162:163]
	v_and_b32_e32 v194, 48, v231
	v_mov_b32_e32 v195, 0
	v_mul_u32_u24_e32 v194, 0x7e, v194
	v_lshl_add_u64 v[196:197], v[166:167], 0, v[194:195]
	global_load_dwordx4 v[60:63], v[196:197], off
	global_load_dwordx4 v[72:75], v[196:197], off offset:16
	global_load_dwordx4 v[76:79], v[196:197], off offset:32
	global_load_dwordx4 v[80:83], v[196:197], off offset:48
	global_load_dwordx4 v[92:95], v[196:197], off offset:64
	global_load_dwordx4 v[96:99], v[196:197], off offset:80
	global_load_dwordx4 v[204:207], v[196:197], off offset:96
	global_load_dwordx4 v[178:181], v[196:197], off offset:112
	s_waitcnt vmcnt(0)
	v_pk_add_f32 v[60:61], v[60:61], v[62:63]
	v_pk_add_f32 v[72:73], v[72:73], v[74:75]
	v_pk_add_f32 v[76:77], v[76:77], v[78:79]
	v_pk_add_f32 v[80:81], v[80:81], v[82:83]
	v_pk_add_f32 v[92:93], v[92:93], v[94:95]
	v_pk_add_f32 v[96:97], v[96:97], v[98:99]
	v_pk_add_f32 v[204:205], v[204:205], v[206:207]
	v_pk_add_f32 v[178:179], v[178:179], v[180:181]
	v_pk_add_f32 v[60:61], v[60:61], v[72:73]
	v_pk_add_f32 v[76:77], v[76:77], v[80:81]
	v_pk_add_f32 v[92:93], v[92:93], v[96:97]
	v_pk_add_f32 v[204:205], v[204:205], v[178:179]
	v_pk_add_f32 v[60:61], v[60:61], v[76:77]
	v_pk_add_f32 v[92:93], v[92:93], v[204:205]
	v_pk_add_f32 v[60:61], v[60:61], v[92:93]
	s_nop 0
	v_pk_mul_f32 v[182:183], v[60:61], s[74:75] op_sel_hi:[1,0]
	s_nop 0
	v_fma_f32 v184, -v182, v182, v183
	v_max_f32_e32 v184, 0, v184
	v_add_f32_e32 v184, 0x3727c5ac, v184
	v_cmp_gt_f32_e32 vcc, s75, v184
	v_mul_f32_e32 v185, 0x4b800000, v184
	s_nop 1
	v_cndmask_b32_e32 v184, v184, v185, vcc
	v_rsq_f32_e32 v184, v184
	s_nop 0
	v_mul_f32_e32 v185, 0x45800000, v184
	v_cndmask_b32_e32 v163, v184, v185, vcc
	v_mov_b32_e32 v162, v182
	v_add_u32_e32 v194, 0x4000, v194
	v_lshl_add_u64 v[196:197], v[166:167], 0, v[194:195]
	global_load_dwordx4 v[60:63], v[196:197], off
	global_load_dwordx4 v[72:75], v[196:197], off offset:16
	global_load_dwordx4 v[76:79], v[196:197], off offset:32
	global_load_dwordx4 v[80:83], v[196:197], off offset:48
	global_load_dwordx4 v[92:95], v[196:197], off offset:64
	global_load_dwordx4 v[96:99], v[196:197], off offset:80
	global_load_dwordx4 v[204:207], v[196:197], off offset:96
	global_load_dwordx4 v[178:181], v[196:197], off offset:112
	s_waitcnt vmcnt(0)
; __device__ __forceinline__ void row_stats(const float* st, int row, int fq, float& mu, float& rs) {
;     const f32x4 a = *(const f32x4*)(st + (size_t)row * 32 + fq * 8), b = *(const f32x4*)(st + (size_t)row * 32 + fq * 8 + 4);
;     float s = (a[0] + a[2]) + (b[0] + b[2]), q = (a[1] + a[3]) + (b[1] + b[3]);
;     s += __shfl_xor(s, 16); s += __shfl_xor(s, 32); q += __shfl_xor(q, 16); q += __shfl_xor(q, 32);
;     mu = s * (1.0f / 1024.0f); const float var = fmaxf(q * (1.0f / 1024.0f) - mu * mu, 0.f); rs = rsqrtf(var + LN_EPS);
;     __device__ __forceinline__ void operator()(const f32x4 (&acc)[2][2][4][2], const Unit& u, int wr, int wc, int fr_, int fq_) const {
;     ...
;             for (int n = 0; n < 2; ++n) { c1v[bj][n] = *(const f32x4*)(c1 + u.pn * 256 + bj * 128 + lc + 4 * n); c2v[bj][n] = *(const f32x4*)(c2 + u.pn * 256 + bj * 128 + lc + 4 * n); }
;         float mus[8], rss[8];
; #pragma unroll
;         for (int q = 0; q < 8; ++q) row_stats(st1, u.pm * 256 + (q >> 2) * 128 + (q & 3) * 16 + wr * 64 + fr, fq, mus[q], rss[q]);
;         asm volatile("" ::: "memory");
; #pragma unroll
;         for (int ai = 0; ai < 2; ++ai)
; #pragma unroll
;             for (int m = 0; m < 4; ++m) {
;                 const int grow = u.pm * 256 + ai * 128 + m * 16 + wr * 64 + fr;
;                 const float mu = mus[ai * 4 + m], rs = rss[ai * 4 + m];
;                 f32x4 h[2];
; #pragma unroll
;                 for (int n = 0; n < 2; ++n) {
;                     const f32x4 g = (acc[ai][0][m][n] - mu * c1v[0][n]) * rs + c2v[0][n];
;                     const f32x4 up = (acc[ai][1][m][n] - mu * c1v[1][n]) * rs + c2v[1][n];
	v_pk_add_f32 v[60:61], v[60:61], v[62:63]
	v_pk_add_f32 v[72:73], v[72:73], v[74:75]
	v_pk_add_f32 v[76:77], v[76:77], v[78:79]
	v_pk_add_f32 v[80:81], v[80:81], v[82:83]
	v_pk_add_f32 v[92:93], v[92:93], v[94:95]
	v_pk_add_f32 v[96:97], v[96:97], v[98:99]
	v_pk_add_f32 v[204:205], v[204:205], v[206:207]
	v_pk_add_f32 v[178:179], v[178:179], v[180:181]
	v_pk_add_f32 v[60:61], v[60:61], v[72:73]
	v_pk_add_f32 v[76:77], v[76:77], v[80:81]
	v_pk_add_f32 v[92:93], v[92:93], v[96:97]
	v_pk_add_f32 v[204:205], v[204:205], v[178:179]
	v_pk_add_f32 v[60:61], v[60:61], v[76:77]
	v_pk_add_f32 v[92:93], v[92:93], v[204:205]
	v_pk_add_f32 v[60:61], v[60:61], v[92:93]
	s_nop 0
	v_pk_mul_f32 v[182:183], v[60:61], s[74:75] op_sel_hi:[1,0]
	s_nop 0
	v_fma_f32 v184, -v182, v182, v183
	v_max_f32_e32 v184, 0, v184
	v_add_f32_e32 v184, 0x3727c5ac, v184
	v_cmp_gt_f32_e32 vcc, s75, v184
	v_mul_f32_e32 v185, 0x4b800000, v184
	s_nop 1
	v_cndmask_b32_e32 v184, v184, v185, vcc
	v_rsq_f32_e32 v184, v184
	s_nop 0
	v_mul_f32_e32 v185, 0x45800000, v184
	v_cndmask_b32_e32 v165, v184, v185, vcc
	v_mov_b32_e32 v164, v182
	global_load_dwordx4 v[72:75], v[64:65], off offset:16
	global_load_dwordx4 v[92:95], v[64:65], off
	global_load_dwordx4 v[76:79], v[84:85], off offset:16
	global_load_dwordx4 v[96:99], v[84:85], off
	global_load_dwordx4 v[60:63], v[64:65], off offset:528
	global_load_dwordx4 v[80:83], v[64:65], off offset:512
	s_nop 0
	global_load_dwordx4 v[64:67], v[84:85], off offset:528
	s_nop 0
	global_load_dwordx4 v[84:87], v[84:85], off offset:512
	v_and_b32_e32 v194, 15, v231
	v_lshlrev_b32_e32 v194, 2, v194
	v_add_u32_e32 v195, 64, v194
	v_add_u32_e32 v196, 0x80, v194
	v_add_u32_e32 v197, 0xc0, v194
	ds_bpermute_b32 v227, v194, v162
	ds_bpermute_b32 v228, v194, v163
	ds_bpermute_b32 v215, v195, v162
	ds_bpermute_b32 v216, v195, v163
	ds_bpermute_b32 v201, v196, v162
	ds_bpermute_b32 v202, v196, v163
	ds_bpermute_b32 v199, v197, v162
	ds_bpermute_b32 v192, v197, v163
	ds_bpermute_b32 v181, v194, v164
	ds_bpermute_b32 v186, v194, v165
	ds_bpermute_b32 v219, v195, v164
	ds_bpermute_b32 v222, v195, v165
	ds_bpermute_b32 v221, v196, v164
	ds_bpermute_b32 v224, v196, v165
	ds_bpermute_b32 v208, v197, v164
	ds_bpermute_b32 v209, v197, v165
	s_waitcnt lgkmcnt(0)
	v_mov_b32_e32 v161, v208
	v_mov_b32_e32 v162, v209
	s_waitcnt vmcnt(0)
	v_add_u32_e32 v204, 16, v210
	v_ashrrev_i32_e32 v205, 31, v204
	v_add_u32_e32 v208, 0x90, v210
	v_ashrrev_i32_e32 v209, 31, v208
	v_add_u32_e32 v212, 0xa0, v210
	v_ashrrev_i32_e32 v213, 31, v212
	s_lshl_b32 s10, s54, 7
	s_ashr_i32 s11, s10, 31
	s_movk_i32 s1, 0x1600
	s_lshl_b64 s[10:11], s[10:11], 1
	s_mov_b32 s54, s0
	s_mov_b32 s5, s38
	v_pk_fma_f32 v[156:157], v[92:93], v[226:227], v[156:157] op_sel:[0,1,0] neg_lo:[1,0,0] neg_hi:[1,0,0]
	v_pk_fma_f32 v[152:153], v[80:81], v[226:227], v[152:153] op_sel:[0,1,0] neg_lo:[1,0,0] neg_hi:[1,0,0]
	v_pk_fma_f32 v[154:155], v[82:83], v[226:227], v[154:155] op_sel:[0,1,0] neg_lo:[1,0,0] neg_hi:[1,0,0]
	v_pk_fma_f32 v[148:149], v[72:73], v[226:227], v[148:149] op_sel:[0,1,0] neg_lo:[1,0,0] neg_hi:[1,0,0]
	v_pk_fma_f32 v[156:157], v[156:157], v[228:229], v[96:97] op_sel_hi:[1,0,1]
	v_pk_fma_f32 v[152:153], v[152:153], v[228:229], v[84:85] op_sel_hi:[1,0,1]
	v_pk_fma_f32 v[154:155], v[154:155], v[228:229], v[86:87] op_sel_hi:[1,0,1]
	v_pk_fma_f32 v[148:149], v[148:149], v[228:229], v[76:77] op_sel_hi:[1,0,1]
	v_pk_fma_f32 v[144:145], v[60:61], v[226:227], v[144:145] op_sel:[0,1,0] neg_lo:[1,0,0] neg_hi:[1,0,0]
	v_pk_fma_f32 v[146:147], v[62:63], v[226:227], v[146:147] op_sel:[0,1,0] neg_lo:[1,0,0] neg_hi:[1,0,0]
	v_pk_fma_f32 v[144:145], v[144:145], v[228:229], v[64:65] op_sel_hi:[1,0,1]
	v_pk_fma_f32 v[146:147], v[146:147], v[228:229], v[66:67] op_sel_hi:[1,0,1]
	v_add_u32_e32 v182, 32, v210
	v_ashrrev_i32_e32 v183, 31, v182
	v_pk_fma_f32 v[140:141], v[92:93], v[214:215], v[140:141] op_sel:[0,1,0] neg_lo:[1,0,0] neg_hi:[1,0,0]
	v_pk_fma_f32 v[136:137], v[80:81], v[214:215], v[136:137] op_sel:[0,1,0] neg_lo:[1,0,0] neg_hi:[1,0,0]
	v_pk_fma_f32 v[138:139], v[82:83], v[214:215], v[138:139] op_sel:[0,1,0] neg_lo:[1,0,0] neg_hi:[1,0,0]
	v_pk_fma_f32 v[132:133], v[72:73], v[214:215], v[132:133] op_sel:[0,1,0] neg_lo:[1,0,0] neg_hi:[1,0,0]
	v_pk_fma_f32 v[140:141], v[140:141], v[216:217], v[96:97] op_sel_hi:[1,0,1]
	v_pk_fma_f32 v[136:137], v[136:137], v[216:217], v[84:85] op_sel_hi:[1,0,1]
	v_pk_fma_f32 v[138:139], v[138:139], v[216:217], v[86:87] op_sel_hi:[1,0,1]
	v_pk_fma_f32 v[132:133], v[132:133], v[216:217], v[76:77] op_sel_hi:[1,0,1]
	v_pk_fma_f32 v[128:129], v[60:61], v[214:215], v[128:129] op_sel:[0,1,0] neg_lo:[1,0,0] neg_hi:[1,0,0]
	v_pk_fma_f32 v[130:131], v[62:63], v[214:215], v[130:131] op_sel:[0,1,0] neg_lo:[1,0,0] neg_hi:[1,0,0]
	v_pk_fma_f32 v[128:129], v[128:129], v[216:217], v[64:65] op_sel_hi:[1,0,1]
	v_pk_fma_f32 v[130:131], v[130:131], v[216:217], v[66:67] op_sel_hi:[1,0,1]
	v_add_u32_e32 v184, 48, v210
	v_ashrrev_i32_e32 v185, 31, v184
	v_pk_fma_f32 v[124:125], v[92:93], v[200:201], v[124:125] op_sel:[0,1,0] neg_lo:[1,0,0] neg_hi:[1,0,0]
	v_pk_fma_f32 v[120:121], v[80:81], v[200:201], v[120:121] op_sel:[0,1,0] neg_lo:[1,0,0] neg_hi:[1,0,0]
	v_pk_fma_f32 v[122:123], v[82:83], v[200:201], v[122:123] op_sel:[0,1,0] neg_lo:[1,0,0] neg_hi:[1,0,0]
	v_pk_fma_f32 v[116:117], v[72:73], v[200:201], v[116:117] op_sel:[0,1,0] neg_lo:[1,0,0] neg_hi:[1,0,0]
	v_pk_fma_f32 v[124:125], v[124:125], v[202:203], v[96:97] op_sel_hi:[1,0,1]
	v_pk_fma_f32 v[120:121], v[120:121], v[202:203], v[84:85] op_sel_hi:[1,0,1]
	v_pk_fma_f32 v[122:123], v[122:123], v[202:203], v[86:87] op_sel_hi:[1,0,1]
; __device__ __forceinline__ float silu_f(float x) { return x * __builtin_amdgcn_rcpf(1.0f + __expf(-x)); }
;     __device__ __forceinline__ void operator()(const f32x4 (&acc)[2][2][4][2], const Unit& u, int wr, int wc, int fr_, int fq_) const {
;     ...
;         for (int ai = 0; ai < 2; ++ai)
; #pragma unroll
;             for (int m = 0; m < 4; ++m) {
;                 const int grow = u.pm * 256 + ai * 128 + m * 16 + wr * 64 + fr;
;                 const float mu = mus[ai * 4 + m], rs = rss[ai * 4 + m];
;                 f32x4 h[2];
; #pragma unroll
;                 for (int n = 0; n < 2; ++n) {
;                     const f32x4 g = (acc[ai][0][m][n] - mu * c1v[0][n]) * rs + c2v[0][n];
;                     const f32x4 up = (acc[ai][1][m][n] - mu * c1v[1][n]) * rs + c2v[1][n];
; #pragma unroll
;                     for (int j = 0; j < 4; ++j) h[n][j] = silu_f(g[j]) * up[j];
	v_pk_fma_f32 v[116:117], v[116:117], v[202:203], v[76:77] op_sel_hi:[1,0,1]
	v_pk_fma_f32 v[112:113], v[60:61], v[200:201], v[112:113] op_sel:[0,1,0] neg_lo:[1,0,0] neg_hi:[1,0,0]
	v_pk_fma_f32 v[114:115], v[62:63], v[200:201], v[114:115] op_sel:[0,1,0] neg_lo:[1,0,0] neg_hi:[1,0,0]
	v_pk_fma_f32 v[112:113], v[112:113], v[202:203], v[64:65] op_sel_hi:[1,0,1]
	v_pk_fma_f32 v[114:115], v[114:115], v[202:203], v[66:67] op_sel_hi:[1,0,1]
	v_add_u32_e32 v178, 0x80, v210
	v_ashrrev_i32_e32 v179, 31, v178
	v_pk_fma_f32 v[108:109], v[92:93], v[198:199], v[108:109] op_sel:[0,1,0] neg_lo:[1,0,0] neg_hi:[1,0,0]
	v_pk_fma_f32 v[104:105], v[80:81], v[198:199], v[104:105] op_sel:[0,1,0] neg_lo:[1,0,0] neg_hi:[1,0,0]
	v_pk_fma_f32 v[106:107], v[82:83], v[198:199], v[106:107] op_sel:[0,1,0] neg_lo:[1,0,0] neg_hi:[1,0,0]
	v_pk_fma_f32 v[100:101], v[72:73], v[198:199], v[100:101] op_sel:[0,1,0] neg_lo:[1,0,0] neg_hi:[1,0,0]
	v_pk_fma_f32 v[108:109], v[108:109], v[192:193], v[96:97] op_sel_hi:[1,0,1]
	v_pk_fma_f32 v[104:105], v[104:105], v[192:193], v[84:85] op_sel_hi:[1,0,1]
	v_pk_fma_f32 v[106:107], v[106:107], v[192:193], v[86:87] op_sel_hi:[1,0,1]
	v_pk_fma_f32 v[100:101], v[100:101], v[192:193], v[76:77] op_sel_hi:[1,0,1]
	v_pk_fma_f32 v[88:89], v[60:61], v[198:199], v[88:89] op_sel:[0,1,0] neg_lo:[1,0,0] neg_hi:[1,0,0]
	v_pk_fma_f32 v[90:91], v[62:63], v[198:199], v[90:91] op_sel:[0,1,0] neg_lo:[1,0,0] neg_hi:[1,0,0]
	v_pk_fma_f32 v[88:89], v[88:89], v[192:193], v[64:65] op_sel_hi:[1,0,1]
	v_pk_fma_f32 v[90:91], v[90:91], v[192:193], v[66:67] op_sel_hi:[1,0,1]
	v_pk_fma_f32 v[68:69], v[92:93], v[180:181], v[68:69] op_sel:[0,1,0] neg_lo:[1,0,0] neg_hi:[1,0,0]
	v_pk_fma_f32 v[56:57], v[80:81], v[180:181], v[56:57] op_sel:[0,1,0] neg_lo:[1,0,0] neg_hi:[1,0,0]
	v_pk_fma_f32 v[58:59], v[82:83], v[180:181], v[58:59] op_sel:[0,1,0] neg_lo:[1,0,0] neg_hi:[1,0,0]
	v_pk_fma_f32 v[52:53], v[72:73], v[180:181], v[52:53] op_sel:[0,1,0] neg_lo:[1,0,0] neg_hi:[1,0,0]
	v_pk_fma_f32 v[68:69], v[68:69], v[186:187], v[96:97] op_sel_hi:[1,0,1]
	v_pk_fma_f32 v[56:57], v[56:57], v[186:187], v[84:85] op_sel_hi:[1,0,1]
	v_pk_fma_f32 v[58:59], v[58:59], v[186:187], v[86:87] op_sel_hi:[1,0,1]
	v_pk_fma_f32 v[52:53], v[52:53], v[186:187], v[76:77] op_sel_hi:[1,0,1]
	v_pk_fma_f32 v[48:49], v[60:61], v[180:181], v[48:49] op_sel:[0,1,0] neg_lo:[1,0,0] neg_hi:[1,0,0]
	v_pk_fma_f32 v[50:51], v[62:63], v[180:181], v[50:51] op_sel:[0,1,0] neg_lo:[1,0,0] neg_hi:[1,0,0]
	v_pk_fma_f32 v[48:49], v[48:49], v[186:187], v[64:65] op_sel_hi:[1,0,1]
	v_pk_fma_f32 v[50:51], v[50:51], v[186:187], v[66:67] op_sel_hi:[1,0,1]
	v_pk_fma_f32 v[44:45], v[92:93], v[218:219], v[44:45] op_sel:[0,1,0] neg_lo:[1,0,0] neg_hi:[1,0,0]
	v_pk_fma_f32 v[40:41], v[80:81], v[218:219], v[40:41] op_sel:[0,1,0] neg_lo:[1,0,0] neg_hi:[1,0,0]
	v_pk_fma_f32 v[42:43], v[82:83], v[218:219], v[42:43] op_sel:[0,1,0] neg_lo:[1,0,0] neg_hi:[1,0,0]
	v_pk_fma_f32 v[36:37], v[72:73], v[218:219], v[36:37] op_sel:[0,1,0] neg_lo:[1,0,0] neg_hi:[1,0,0]
	v_pk_fma_f32 v[44:45], v[44:45], v[222:223], v[96:97] op_sel_hi:[1,0,1]
	v_pk_fma_f32 v[40:41], v[40:41], v[222:223], v[84:85] op_sel_hi:[1,0,1]
	v_pk_fma_f32 v[42:43], v[42:43], v[222:223], v[86:87] op_sel_hi:[1,0,1]
	v_pk_fma_f32 v[36:37], v[36:37], v[222:223], v[76:77] op_sel_hi:[1,0,1]
	v_pk_fma_f32 v[32:33], v[60:61], v[218:219], v[32:33] op_sel:[0,1,0] neg_lo:[1,0,0] neg_hi:[1,0,0]
	v_pk_fma_f32 v[34:35], v[62:63], v[218:219], v[34:35] op_sel:[0,1,0] neg_lo:[1,0,0] neg_hi:[1,0,0]
	v_pk_fma_f32 v[32:33], v[32:33], v[222:223], v[64:65] op_sel_hi:[1,0,1]
	v_pk_fma_f32 v[34:35], v[34:35], v[222:223], v[66:67] op_sel_hi:[1,0,1]
	v_add_u32_e32 v206, 0xb0, v210
	v_ashrrev_i32_e32 v207, 31, v206
	v_pk_fma_f32 v[28:29], v[92:93], v[220:221], v[28:29] op_sel:[0,1,0] neg_lo:[1,0,0] neg_hi:[1,0,0]
	v_pk_fma_f32 v[24:25], v[80:81], v[220:221], v[24:25] op_sel:[0,1,0] neg_lo:[1,0,0] neg_hi:[1,0,0]
	v_pk_fma_f32 v[26:27], v[82:83], v[220:221], v[26:27] op_sel:[0,1,0] neg_lo:[1,0,0] neg_hi:[1,0,0]
	v_pk_fma_f32 v[20:21], v[72:73], v[220:221], v[20:21] op_sel:[0,1,0] neg_lo:[1,0,0] neg_hi:[1,0,0]
	v_pk_fma_f32 v[28:29], v[28:29], v[224:225], v[96:97] op_sel_hi:[1,0,1]
	v_pk_fma_f32 v[24:25], v[24:25], v[224:225], v[84:85] op_sel_hi:[1,0,1]
	v_pk_fma_f32 v[26:27], v[26:27], v[224:225], v[86:87] op_sel_hi:[1,0,1]
	v_pk_fma_f32 v[20:21], v[20:21], v[224:225], v[76:77] op_sel_hi:[1,0,1]
	v_pk_fma_f32 v[16:17], v[60:61], v[220:221], v[16:17] op_sel:[0,1,0] neg_lo:[1,0,0] neg_hi:[1,0,0]
	v_pk_fma_f32 v[18:19], v[62:63], v[220:221], v[18:19] op_sel:[0,1,0] neg_lo:[1,0,0] neg_hi:[1,0,0]
	v_pk_fma_f32 v[16:17], v[16:17], v[224:225], v[64:65] op_sel_hi:[1,0,1]
	v_pk_fma_f32 v[18:19], v[18:19], v[224:225], v[66:67] op_sel_hi:[1,0,1]
	v_pk_fma_f32 v[12:13], v[92:93], v[160:161], v[12:13] op_sel:[0,1,0] neg_lo:[1,0,0] neg_hi:[1,0,0]
	v_pk_fma_f32 v[8:9], v[80:81], v[160:161], v[8:9] op_sel:[0,1,0] neg_lo:[1,0,0] neg_hi:[1,0,0]
	v_pk_fma_f32 v[10:11], v[82:83], v[160:161], v[10:11] op_sel:[0,1,0] neg_lo:[1,0,0] neg_hi:[1,0,0]
	v_pk_fma_f32 v[4:5], v[72:73], v[160:161], v[4:5] op_sel:[0,1,0] neg_lo:[1,0,0] neg_hi:[1,0,0]
	v_mul_f32_e32 v163, 0xbfb8aa3b, v156
	v_exp_f32_e32 v163, v163
	v_pk_fma_f32 v[0:1], v[60:61], v[160:161], v[0:1] op_sel:[0,1,0] neg_lo:[1,0,0] neg_hi:[1,0,0]
	v_pk_fma_f32 v[2:3], v[62:63], v[160:161], v[2:3] op_sel:[0,1,0] neg_lo:[1,0,0] neg_hi:[1,0,0]
	s_and_b64 vcc, exec, s[40:41]
	v_add_f32_e32 v163, 1.0, v163
	v_rcp_f32_e32 v164, v163
	v_mul_f32_e32 v163, 0xbfb8aa3b, v157
	v_exp_f32_e32 v163, v163
	s_nop 0
	v_add_f32_e32 v163, 1.0, v163
	v_rcp_f32_e32 v165, v163
; __device__ __forceinline__ float silu_f(float x) { return x * __builtin_amdgcn_rcpf(1.0f + __expf(-x)); }
; __device__ __forceinline__ u32x4 pack8(const f32x4 a, const f32x4 b) { u32x4 w; w.x = cvt_pk_bf16(a[0], a[1]); w.y = cvt_pk_bf16(a[2], a[3]); w.z = cvt_pk_bf16(b[0], b[1]); w.w = cvt_pk_bf16(b[2], b[3]); return w; }
;     __device__ __forceinline__ void operator()(const f32x4 (&acc)[2][2][4][2], const Unit& u, int wr, int wc, int fr_, int fq_) const {
;     ...
;         for (int ai = 0; ai < 2; ++ai)
; #pragma unroll
;             for (int m = 0; m < 4; ++m) {
;                 const int grow = u.pm * 256 + ai * 128 + m * 16 + wr * 64 + fr;
;                 const float mu = mus[ai * 4 + m], rs = rss[ai * 4 + m];
;                 f32x4 h[2];
; #pragma unroll
;                 for (int n = 0; n < 2; ++n) {
;                     const f32x4 g = (acc[ai][0][m][n] - mu * c1v[0][n]) * rs + c2v[0][n];
;                     const f32x4 up = (acc[ai][1][m][n] - mu * c1v[1][n]) * rs + c2v[1][n];
; #pragma unroll
;                     for (int j = 0; j < 4; ++j) h[n][j] = silu_f(g[j]) * up[j];
;                 }
;                 *(u32x4*)(H + (size_t)grow * KF2 + u.pn * 128 + lc) = pack8(h[0], h[1]);
	v_pk_fma_f32 v[12:13], v[12:13], v[162:163], v[96:97] op_sel_hi:[1,0,1]
	v_pk_fma_f32 v[8:9], v[8:9], v[162:163], v[84:85] op_sel_hi:[1,0,1]
	v_pk_fma_f32 v[10:11], v[10:11], v[162:163], v[86:87] op_sel_hi:[1,0,1]
	v_pk_mul_f32 v[156:157], v[156:157], v[164:165]
	v_pk_fma_f32 v[4:5], v[4:5], v[162:163], v[76:77] op_sel_hi:[1,0,1]
	v_pk_mul_f32 v[152:153], v[152:153], v[156:157]
	v_pk_fma_f32 v[156:157], v[94:95], v[226:227], v[158:159] op_sel:[0,1,0] neg_lo:[1,0,0] neg_hi:[1,0,0]
	v_pk_fma_f32 v[0:1], v[0:1], v[162:163], v[64:65] op_sel_hi:[1,0,1]
	v_pk_fma_f32 v[156:157], v[156:157], v[228:229], v[98:99] op_sel_hi:[1,0,1]
	v_pk_fma_f32 v[2:3], v[2:3], v[162:163], v[66:67] op_sel_hi:[1,0,1]
	v_mul_f32_e32 v158, 0xbfb8aa3b, v156
	v_mul_f32_e32 v159, 0xbfb8aa3b, v157
	v_exp_f32_e32 v158, v158
	v_exp_f32_e32 v159, v159
	v_add_f32_e32 v158, 1.0, v158
	v_add_f32_e32 v159, 1.0, v159
	v_rcp_f32_e32 v158, v158
	v_rcp_f32_e32 v159, v159
	s_nop 0
	v_pk_mul_f32 v[156:157], v[156:157], v[158:159]
	s_nop 0
	v_pk_mul_f32 v[154:155], v[154:155], v[156:157]
	v_mul_f32_e32 v156, 0xbfb8aa3b, v148
	v_mul_f32_e32 v157, 0xbfb8aa3b, v149
	v_exp_f32_e32 v156, v156
	v_exp_f32_e32 v157, v157
	v_add_f32_e32 v156, 1.0, v156
	v_add_f32_e32 v157, 1.0, v157
	v_rcp_f32_e32 v156, v156
	v_rcp_f32_e32 v157, v157
	s_nop 0
	v_pk_mul_f32 v[148:149], v[148:149], v[156:157]
	s_nop 0
	v_pk_mul_f32 v[144:145], v[144:145], v[148:149]
	v_pk_fma_f32 v[148:149], v[74:75], v[226:227], v[150:151] op_sel:[0,1,0] neg_lo:[1,0,0] neg_hi:[1,0,0]
	s_nop 0
	v_pk_fma_f32 v[148:149], v[148:149], v[228:229], v[78:79] op_sel_hi:[1,0,1]
	s_nop 0
	v_mul_f32_e32 v150, 0xbfb8aa3b, v148
	v_mul_f32_e32 v151, 0xbfb8aa3b, v149
	v_exp_f32_e32 v150, v150
	v_exp_f32_e32 v151, v151
	v_add_f32_e32 v150, 1.0, v150
	v_add_f32_e32 v151, 1.0, v151
	v_rcp_f32_e32 v150, v150
	v_rcp_f32_e32 v151, v151
	s_nop 0
	v_pk_mul_f32 v[148:149], v[148:149], v[150:151]
	s_nop 0
	v_pk_mul_f32 v[146:147], v[146:147], v[148:149]
	v_cvt_pk_bf16_f32 v150, v144, v145
	v_mov_b64_e32 v[144:145], s[24:25]
	v_cvt_pk_bf16_f32 v151, v146, v147
	v_mad_i64_i32 v[146:147], s[14:15], v210, s1, v[144:145]
	v_cvt_pk_bf16_f32 v148, v152, v153
	v_lshl_add_u64 v[152:153], v[146:147], 0, s[10:11]
	v_lshlrev_b64 v[146:147], 1, v[188:189]
	v_cvt_pk_bf16_f32 v149, v154, v155
	v_lshl_add_u64 v[152:153], v[152:153], 0, v[146:147]
	global_store_dwordx4 v[152:153], v[148:151], off
	s_nop 1
	v_mul_f32_e32 v148, 0xbfb8aa3b, v140
	v_mul_f32_e32 v149, 0xbfb8aa3b, v141
	v_exp_f32_e32 v148, v148
	v_exp_f32_e32 v149, v149
	v_add_f32_e32 v148, 1.0, v148
	v_add_f32_e32 v149, 1.0, v149
	v_rcp_f32_e32 v148, v148
	v_rcp_f32_e32 v149, v149
	s_nop 0
	v_pk_mul_f32 v[140:141], v[140:141], v[148:149]
	s_nop 0
	v_pk_mul_f32 v[136:137], v[136:137], v[140:141]
	v_pk_fma_f32 v[140:141], v[94:95], v[214:215], v[142:143] op_sel:[0,1,0] neg_lo:[1,0,0] neg_hi:[1,0,0]
	s_nop 0
	v_pk_fma_f32 v[140:141], v[140:141], v[216:217], v[98:99] op_sel_hi:[1,0,1]
	s_nop 0
	v_mul_f32_e32 v142, 0xbfb8aa3b, v140
	v_mul_f32_e32 v143, 0xbfb8aa3b, v141
	v_exp_f32_e32 v142, v142
	v_exp_f32_e32 v143, v143
	v_add_f32_e32 v142, 1.0, v142
	v_add_f32_e32 v143, 1.0, v143
	v_rcp_f32_e32 v142, v142
	v_rcp_f32_e32 v143, v143
	s_nop 0
	v_pk_mul_f32 v[140:141], v[140:141], v[142:143]
	s_nop 0
	v_pk_mul_f32 v[138:139], v[138:139], v[140:141]
	v_mul_f32_e32 v140, 0xbfb8aa3b, v132
	v_mul_f32_e32 v141, 0xbfb8aa3b, v133
	v_exp_f32_e32 v140, v140
	v_exp_f32_e32 v141, v141
	v_add_f32_e32 v140, 1.0, v140
	v_add_f32_e32 v141, 1.0, v141
	v_rcp_f32_e32 v140, v140
	v_rcp_f32_e32 v141, v141
	s_nop 0
	v_pk_mul_f32 v[132:133], v[132:133], v[140:141]
	s_nop 0
	v_pk_mul_f32 v[132:133], v[128:129], v[132:133]
	v_pk_fma_f32 v[128:129], v[74:75], v[214:215], v[134:135] op_sel:[0,1,0] neg_lo:[1,0,0] neg_hi:[1,0,0]
	s_nop 0
	v_pk_fma_f32 v[128:129], v[128:129], v[216:217], v[78:79] op_sel_hi:[1,0,1]
	s_nop 0
	v_mul_f32_e32 v134, 0xbfb8aa3b, v128
	v_mul_f32_e32 v135, 0xbfb8aa3b, v129
	v_exp_f32_e32 v134, v134
	v_exp_f32_e32 v135, v135
	v_add_f32_e32 v134, 1.0, v134
	v_add_f32_e32 v135, 1.0, v135
	v_rcp_f32_e32 v134, v134
	v_rcp_f32_e32 v135, v135
	s_nop 0
	v_pk_mul_f32 v[128:129], v[128:129], v[134:135]
	s_nop 0
	v_pk_mul_f32 v[134:135], v[130:131], v[128:129]
	v_cvt_pk_bf16_f32 v130, v132, v133
	v_mad_i64_i32 v[132:133], s[14:15], v204, s1, v[144:145]
	v_lshl_add_u64 v[132:133], v[132:133], 0, s[10:11]
	v_cvt_pk_bf16_f32 v128, v136, v137
	v_cvt_pk_bf16_f32 v129, v138, v139
	v_cvt_pk_bf16_f32 v131, v134, v135
	v_lshl_add_u64 v[132:133], v[132:133], 0, v[146:147]
	global_store_dwordx4 v[132:133], v[128:131], off
	s_nop 1
	v_mul_f32_e32 v128, 0xbfb8aa3b, v124
	v_mul_f32_e32 v129, 0xbfb8aa3b, v125
	v_exp_f32_e32 v128, v128
	v_exp_f32_e32 v129, v129
	v_add_f32_e32 v128, 1.0, v128
	v_add_f32_e32 v129, 1.0, v129
	v_rcp_f32_e32 v128, v128
	v_rcp_f32_e32 v129, v129
	s_nop 0
	v_pk_mul_f32 v[124:125], v[124:125], v[128:129]
	s_nop 0
	v_pk_mul_f32 v[120:121], v[120:121], v[124:125]
	v_pk_fma_f32 v[124:125], v[94:95], v[200:201], v[126:127] op_sel:[0,1,0] neg_lo:[1,0,0] neg_hi:[1,0,0]
	s_nop 0
	v_pk_fma_f32 v[124:125], v[124:125], v[202:203], v[98:99] op_sel_hi:[1,0,1]
	s_nop 0
	v_mul_f32_e32 v126, 0xbfb8aa3b, v124
	v_mul_f32_e32 v127, 0xbfb8aa3b, v125
	v_exp_f32_e32 v126, v126
	v_exp_f32_e32 v127, v127
	v_add_f32_e32 v126, 1.0, v126
	v_add_f32_e32 v127, 1.0, v127
	v_rcp_f32_e32 v126, v126
	v_rcp_f32_e32 v127, v127
	s_nop 0
	v_pk_mul_f32 v[124:125], v[124:125], v[126:127]
	s_nop 0
	v_pk_mul_f32 v[122:123], v[122:123], v[124:125]
	v_mul_f32_e32 v124, 0xbfb8aa3b, v116
	v_mul_f32_e32 v125, 0xbfb8aa3b, v117
	v_exp_f32_e32 v124, v124
; __device__ __forceinline__ float silu_f(float x) { return x * __builtin_amdgcn_rcpf(1.0f + __expf(-x)); }
; __device__ __forceinline__ u32x4 pack8(const f32x4 a, const f32x4 b) { u32x4 w; w.x = cvt_pk_bf16(a[0], a[1]); w.y = cvt_pk_bf16(a[2], a[3]); w.z = cvt_pk_bf16(b[0], b[1]); w.w = cvt_pk_bf16(b[2], b[3]); return w; }
;     __device__ __forceinline__ void operator()(const f32x4 (&acc)[2][2][4][2], const Unit& u, int wr, int wc, int fr_, int fq_) const {
;     ...
;         for (int ai = 0; ai < 2; ++ai)
; #pragma unroll
;             for (int m = 0; m < 4; ++m) {
;                 const int grow = u.pm * 256 + ai * 128 + m * 16 + wr * 64 + fr;
;                 const float mu = mus[ai * 4 + m], rs = rss[ai * 4 + m];
;                 f32x4 h[2];
; #pragma unroll
;                 for (int n = 0; n < 2; ++n) {
;                     const f32x4 g = (acc[ai][0][m][n] - mu * c1v[0][n]) * rs + c2v[0][n];
;                     const f32x4 up = (acc[ai][1][m][n] - mu * c1v[1][n]) * rs + c2v[1][n];
; #pragma unroll
;                     for (int j = 0; j < 4; ++j) h[n][j] = silu_f(g[j]) * up[j];
;                 }
;                 *(u32x4*)(H + (size_t)grow * KF2 + u.pn * 128 + lc) = pack8(h[0], h[1]);
	v_exp_f32_e32 v125, v125
	v_add_f32_e32 v124, 1.0, v124
	v_add_f32_e32 v125, 1.0, v125
	v_rcp_f32_e32 v124, v124
	v_rcp_f32_e32 v125, v125
	s_nop 0
	v_pk_mul_f32 v[116:117], v[116:117], v[124:125]
	s_nop 0
	v_pk_mul_f32 v[116:117], v[112:113], v[116:117]
	v_pk_fma_f32 v[112:113], v[74:75], v[200:201], v[118:119] op_sel:[0,1,0] neg_lo:[1,0,0] neg_hi:[1,0,0]
	s_nop 0
	v_pk_fma_f32 v[112:113], v[112:113], v[202:203], v[78:79] op_sel_hi:[1,0,1]
	s_nop 0
	v_mul_f32_e32 v118, 0xbfb8aa3b, v112
	v_mul_f32_e32 v119, 0xbfb8aa3b, v113
	v_exp_f32_e32 v118, v118
	v_exp_f32_e32 v119, v119
	v_add_f32_e32 v118, 1.0, v118
	v_add_f32_e32 v119, 1.0, v119
	v_rcp_f32_e32 v118, v118
	v_rcp_f32_e32 v119, v119
	s_nop 0
	v_pk_mul_f32 v[112:113], v[112:113], v[118:119]
	s_nop 0
	v_pk_mul_f32 v[118:119], v[114:115], v[112:113]
	v_cvt_pk_bf16_f32 v114, v116, v117
	v_mad_i64_i32 v[116:117], s[14:15], v182, s1, v[144:145]
	v_lshl_add_u64 v[116:117], v[116:117], 0, s[10:11]
	v_cvt_pk_bf16_f32 v112, v120, v121
	v_cvt_pk_bf16_f32 v113, v122, v123
	v_cvt_pk_bf16_f32 v115, v118, v119
	v_lshl_add_u64 v[116:117], v[116:117], 0, v[146:147]
	global_store_dwordx4 v[116:117], v[112:115], off
	s_nop 1
	v_mul_f32_e32 v112, 0xbfb8aa3b, v108
	v_mul_f32_e32 v113, 0xbfb8aa3b, v109
	v_exp_f32_e32 v112, v112
	v_exp_f32_e32 v113, v113
	v_add_f32_e32 v112, 1.0, v112
	v_add_f32_e32 v113, 1.0, v113
	v_rcp_f32_e32 v112, v112
	v_rcp_f32_e32 v113, v113
	s_nop 0
	v_pk_mul_f32 v[108:109], v[108:109], v[112:113]
	s_nop 0
	v_pk_mul_f32 v[104:105], v[104:105], v[108:109]
	v_pk_fma_f32 v[108:109], v[94:95], v[198:199], v[110:111] op_sel:[0,1,0] neg_lo:[1,0,0] neg_hi:[1,0,0]
	s_nop 0
	v_pk_fma_f32 v[108:109], v[108:109], v[192:193], v[98:99] op_sel_hi:[1,0,1]
	s_nop 0
	v_mul_f32_e32 v110, 0xbfb8aa3b, v108
	v_mul_f32_e32 v111, 0xbfb8aa3b, v109
	v_exp_f32_e32 v110, v110
	v_exp_f32_e32 v111, v111
	v_add_f32_e32 v110, 1.0, v110
	v_add_f32_e32 v111, 1.0, v111
	v_rcp_f32_e32 v110, v110
	v_rcp_f32_e32 v111, v111
	s_nop 0
	v_pk_mul_f32 v[108:109], v[108:109], v[110:111]
	s_nop 0
	v_pk_mul_f32 v[106:107], v[106:107], v[108:109]
	v_mul_f32_e32 v108, 0xbfb8aa3b, v100
	v_mul_f32_e32 v109, 0xbfb8aa3b, v101
	v_exp_f32_e32 v108, v108
	v_exp_f32_e32 v109, v109
	v_add_f32_e32 v108, 1.0, v108
	v_add_f32_e32 v109, 1.0, v109
	v_rcp_f32_e32 v108, v108
	v_rcp_f32_e32 v109, v109
	s_nop 0
	v_pk_mul_f32 v[100:101], v[100:101], v[108:109]
	s_nop 0
	v_pk_mul_f32 v[100:101], v[88:89], v[100:101]
	v_pk_fma_f32 v[88:89], v[74:75], v[198:199], v[102:103] op_sel:[0,1,0] neg_lo:[1,0,0] neg_hi:[1,0,0]
	s_nop 0
	v_pk_fma_f32 v[88:89], v[88:89], v[192:193], v[78:79] op_sel_hi:[1,0,1]
	s_nop 0
	v_mul_f32_e32 v102, 0xbfb8aa3b, v88
	v_mul_f32_e32 v103, 0xbfb8aa3b, v89
	v_exp_f32_e32 v102, v102
	v_exp_f32_e32 v103, v103
	v_add_f32_e32 v102, 1.0, v102
	v_add_f32_e32 v103, 1.0, v103
	v_rcp_f32_e32 v102, v102
	v_rcp_f32_e32 v103, v103
	s_nop 0
	v_pk_mul_f32 v[88:89], v[88:89], v[102:103]
	s_nop 0
	v_pk_mul_f32 v[102:103], v[90:91], v[88:89]
	v_cvt_pk_bf16_f32 v90, v100, v101
	v_mad_i64_i32 v[100:101], s[14:15], v184, s1, v[144:145]
	v_lshl_add_u64 v[100:101], v[100:101], 0, s[10:11]
	v_cvt_pk_bf16_f32 v88, v104, v105
	v_cvt_pk_bf16_f32 v89, v106, v107
	v_cvt_pk_bf16_f32 v91, v102, v103
	v_lshl_add_u64 v[100:101], v[100:101], 0, v[146:147]
	global_store_dwordx4 v[100:101], v[88:91], off
	s_nop 1
	v_mul_f32_e32 v88, 0xbfb8aa3b, v68
	v_mul_f32_e32 v89, 0xbfb8aa3b, v69
	v_exp_f32_e32 v88, v88
	v_exp_f32_e32 v89, v89
	v_add_f32_e32 v88, 1.0, v88
	v_add_f32_e32 v89, 1.0, v89
	v_rcp_f32_e32 v88, v88
	v_rcp_f32_e32 v89, v89
	s_nop 0
	v_pk_mul_f32 v[68:69], v[68:69], v[88:89]
	s_nop 0
	v_pk_mul_f32 v[56:57], v[56:57], v[68:69]
	v_pk_fma_f32 v[68:69], v[94:95], v[180:181], v[70:71] op_sel:[0,1,0] neg_lo:[1,0,0] neg_hi:[1,0,0]
	s_nop 0
	v_pk_fma_f32 v[68:69], v[68:69], v[186:187], v[98:99] op_sel_hi:[1,0,1]
	s_nop 0
	v_mul_f32_e32 v70, 0xbfb8aa3b, v68
	v_mul_f32_e32 v71, 0xbfb8aa3b, v69
	v_exp_f32_e32 v70, v70
	v_exp_f32_e32 v71, v71
	v_add_f32_e32 v70, 1.0, v70
	v_add_f32_e32 v71, 1.0, v71
	v_rcp_f32_e32 v70, v70
	v_rcp_f32_e32 v71, v71
	s_nop 0
	v_pk_mul_f32 v[68:69], v[68:69], v[70:71]
	s_nop 0
	v_pk_mul_f32 v[58:59], v[58:59], v[68:69]
	v_mul_f32_e32 v68, 0xbfb8aa3b, v52
	v_mul_f32_e32 v69, 0xbfb8aa3b, v53
	v_exp_f32_e32 v68, v68
	v_exp_f32_e32 v69, v69
	v_add_f32_e32 v68, 1.0, v68
	v_add_f32_e32 v69, 1.0, v69
	v_rcp_f32_e32 v68, v68
	v_rcp_f32_e32 v69, v69
	s_nop 0
	v_pk_mul_f32 v[52:53], v[52:53], v[68:69]
	s_nop 0
	v_pk_mul_f32 v[52:53], v[48:49], v[52:53]
	v_pk_fma_f32 v[48:49], v[74:75], v[180:181], v[54:55] op_sel:[0,1,0] neg_lo:[1,0,0] neg_hi:[1,0,0]
	s_nop 0
	v_pk_fma_f32 v[48:49], v[48:49], v[186:187], v[78:79] op_sel_hi:[1,0,1]
	s_nop 0
	v_mul_f32_e32 v54, 0xbfb8aa3b, v48
	v_mul_f32_e32 v55, 0xbfb8aa3b, v49
	v_exp_f32_e32 v54, v54
	v_exp_f32_e32 v55, v55
	v_add_f32_e32 v54, 1.0, v54
	v_add_f32_e32 v55, 1.0, v55
	v_rcp_f32_e32 v54, v54
	v_rcp_f32_e32 v55, v55
	s_nop 0
	v_pk_mul_f32 v[48:49], v[48:49], v[54:55]
	s_nop 0
	v_pk_mul_f32 v[54:55], v[50:51], v[48:49]
	v_cvt_pk_bf16_f32 v50, v52, v53
	v_mad_i64_i32 v[52:53], s[14:15], v178, s1, v[144:145]
	v_lshl_add_u64 v[52:53], v[52:53], 0, s[10:11]
	v_cvt_pk_bf16_f32 v48, v56, v57
	v_cvt_pk_bf16_f32 v49, v58, v59
	v_cvt_pk_bf16_f32 v51, v54, v55
	v_lshl_add_u64 v[52:53], v[52:53], 0, v[146:147]
	global_store_dwordx4 v[52:53], v[48:51], off
	s_nop 1
	v_mul_f32_e32 v48, 0xbfb8aa3b, v44
	v_mul_f32_e32 v49, 0xbfb8aa3b, v45
	v_exp_f32_e32 v48, v48
	v_exp_f32_e32 v49, v49
	v_add_f32_e32 v48, 1.0, v48
	v_add_f32_e32 v49, 1.0, v49
	v_rcp_f32_e32 v48, v48
	v_rcp_f32_e32 v49, v49
	s_nop 0
; __device__ __forceinline__ float silu_f(float x) { return x * __builtin_amdgcn_rcpf(1.0f + __expf(-x)); }
; __device__ __forceinline__ u32x4 pack8(const f32x4 a, const f32x4 b) { u32x4 w; w.x = cvt_pk_bf16(a[0], a[1]); w.y = cvt_pk_bf16(a[2], a[3]); w.z = cvt_pk_bf16(b[0], b[1]); w.w = cvt_pk_bf16(b[2], b[3]); return w; }
; template <class Epi>
; __device__ __forceinline__ void gemm_phase(LAS unsigned char* lds, const Gemm g, const StaticOrder& S, const Epi& E) {
;     ...
;         E(acc, cur, wr, wc, fr, fq);
;         if (!has_next) break;
;     __device__ __forceinline__ void operator()(const f32x4 (&acc)[2][2][4][2], const Unit& u, int wr, int wc, int fr_, int fq_) const {
;     ...
;         for (int ai = 0; ai < 2; ++ai)
; #pragma unroll
;             for (int m = 0; m < 4; ++m) {
;                 const int grow = u.pm * 256 + ai * 128 + m * 16 + wr * 64 + fr;
;                 const float mu = mus[ai * 4 + m], rs = rss[ai * 4 + m];
;                 f32x4 h[2];
; #pragma unroll
;                 for (int n = 0; n < 2; ++n) {
;                     const f32x4 g = (acc[ai][0][m][n] - mu * c1v[0][n]) * rs + c2v[0][n];
;                     const f32x4 up = (acc[ai][1][m][n] - mu * c1v[1][n]) * rs + c2v[1][n];
; #pragma unroll
;                     for (int j = 0; j < 4; ++j) h[n][j] = silu_f(g[j]) * up[j];
;                 }
;                 *(u32x4*)(H + (size_t)grow * KF2 + u.pn * 128 + lc) = pack8(h[0], h[1]);
	v_pk_mul_f32 v[44:45], v[44:45], v[48:49]
	s_nop 0
	v_pk_mul_f32 v[40:41], v[40:41], v[44:45]
	v_pk_fma_f32 v[44:45], v[94:95], v[218:219], v[46:47] op_sel:[0,1,0] neg_lo:[1,0,0] neg_hi:[1,0,0]
	s_nop 0
	v_pk_fma_f32 v[44:45], v[44:45], v[222:223], v[98:99] op_sel_hi:[1,0,1]
	s_nop 0
	v_mul_f32_e32 v46, 0xbfb8aa3b, v44
	v_mul_f32_e32 v47, 0xbfb8aa3b, v45
	v_exp_f32_e32 v46, v46
	v_exp_f32_e32 v47, v47
	v_add_f32_e32 v46, 1.0, v46
	v_add_f32_e32 v47, 1.0, v47
	v_rcp_f32_e32 v46, v46
	v_rcp_f32_e32 v47, v47
	s_nop 0
	v_pk_mul_f32 v[44:45], v[44:45], v[46:47]
	s_nop 0
	v_pk_mul_f32 v[42:43], v[42:43], v[44:45]
	v_mul_f32_e32 v44, 0xbfb8aa3b, v36
	v_mul_f32_e32 v45, 0xbfb8aa3b, v37
	v_exp_f32_e32 v44, v44
	v_exp_f32_e32 v45, v45
	v_add_f32_e32 v44, 1.0, v44
	v_add_f32_e32 v45, 1.0, v45
	v_rcp_f32_e32 v44, v44
	v_rcp_f32_e32 v45, v45
	s_nop 0
	v_pk_mul_f32 v[36:37], v[36:37], v[44:45]
	s_nop 0
	v_pk_mul_f32 v[36:37], v[32:33], v[36:37]
	v_pk_fma_f32 v[32:33], v[74:75], v[218:219], v[38:39] op_sel:[0,1,0] neg_lo:[1,0,0] neg_hi:[1,0,0]
	s_nop 0
	v_pk_fma_f32 v[32:33], v[32:33], v[222:223], v[78:79] op_sel_hi:[1,0,1]
	s_nop 0
	v_mul_f32_e32 v38, 0xbfb8aa3b, v32
	v_mul_f32_e32 v39, 0xbfb8aa3b, v33
	v_exp_f32_e32 v38, v38
	v_exp_f32_e32 v39, v39
	v_add_f32_e32 v38, 1.0, v38
	v_add_f32_e32 v39, 1.0, v39
	v_rcp_f32_e32 v38, v38
	v_rcp_f32_e32 v39, v39
	s_nop 0
	v_pk_mul_f32 v[32:33], v[32:33], v[38:39]
	s_nop 0
	v_pk_mul_f32 v[38:39], v[34:35], v[32:33]
	v_cvt_pk_bf16_f32 v34, v36, v37
	v_mad_i64_i32 v[36:37], s[14:15], v208, s1, v[144:145]
	v_lshl_add_u64 v[36:37], v[36:37], 0, s[10:11]
	v_cvt_pk_bf16_f32 v32, v40, v41
	v_cvt_pk_bf16_f32 v33, v42, v43
	v_cvt_pk_bf16_f32 v35, v38, v39
	v_lshl_add_u64 v[36:37], v[36:37], 0, v[146:147]
	global_store_dwordx4 v[36:37], v[32:35], off
	s_nop 1
	v_mul_f32_e32 v32, 0xbfb8aa3b, v28
	v_mul_f32_e32 v33, 0xbfb8aa3b, v29
	v_exp_f32_e32 v32, v32
	v_exp_f32_e32 v33, v33
	v_add_f32_e32 v32, 1.0, v32
	v_add_f32_e32 v33, 1.0, v33
	v_rcp_f32_e32 v32, v32
	v_rcp_f32_e32 v33, v33
	s_nop 0
	v_pk_mul_f32 v[28:29], v[28:29], v[32:33]
	s_nop 0
	v_pk_mul_f32 v[24:25], v[24:25], v[28:29]
	v_pk_fma_f32 v[28:29], v[94:95], v[220:221], v[30:31] op_sel:[0,1,0] neg_lo:[1,0,0] neg_hi:[1,0,0]
	s_nop 0
	v_pk_fma_f32 v[28:29], v[28:29], v[224:225], v[98:99] op_sel_hi:[1,0,1]
	s_nop 0
	v_mul_f32_e32 v30, 0xbfb8aa3b, v28
	v_mul_f32_e32 v31, 0xbfb8aa3b, v29
	v_exp_f32_e32 v30, v30
	v_exp_f32_e32 v31, v31
	v_add_f32_e32 v30, 1.0, v30
	v_add_f32_e32 v31, 1.0, v31
	v_rcp_f32_e32 v30, v30
	v_rcp_f32_e32 v31, v31
	s_nop 0
	v_pk_mul_f32 v[28:29], v[28:29], v[30:31]
	s_nop 0
	v_pk_mul_f32 v[26:27], v[26:27], v[28:29]
	v_mul_f32_e32 v28, 0xbfb8aa3b, v20
	v_mul_f32_e32 v29, 0xbfb8aa3b, v21
	v_exp_f32_e32 v28, v28
	v_exp_f32_e32 v29, v29
	v_add_f32_e32 v28, 1.0, v28
	v_add_f32_e32 v29, 1.0, v29
	v_rcp_f32_e32 v28, v28
	v_rcp_f32_e32 v29, v29
	s_nop 0
	v_pk_mul_f32 v[20:21], v[20:21], v[28:29]
	s_nop 0
	v_pk_mul_f32 v[20:21], v[16:17], v[20:21]
	v_pk_fma_f32 v[16:17], v[74:75], v[220:221], v[22:23] op_sel:[0,1,0] neg_lo:[1,0,0] neg_hi:[1,0,0]
	s_nop 0
	v_pk_fma_f32 v[16:17], v[16:17], v[224:225], v[78:79] op_sel_hi:[1,0,1]
	s_nop 0
	v_mul_f32_e32 v22, 0xbfb8aa3b, v16
	v_mul_f32_e32 v23, 0xbfb8aa3b, v17
	v_exp_f32_e32 v22, v22
	v_exp_f32_e32 v23, v23
	v_add_f32_e32 v22, 1.0, v22
	v_add_f32_e32 v23, 1.0, v23
	v_rcp_f32_e32 v22, v22
	v_rcp_f32_e32 v23, v23
	s_nop 0
	v_pk_mul_f32 v[16:17], v[16:17], v[22:23]
	s_nop 0
	v_pk_mul_f32 v[22:23], v[18:19], v[16:17]
	v_cvt_pk_bf16_f32 v18, v20, v21
	v_mad_i64_i32 v[20:21], s[14:15], v212, s1, v[144:145]
	v_lshl_add_u64 v[20:21], v[20:21], 0, s[10:11]
	v_cvt_pk_bf16_f32 v16, v24, v25
	v_cvt_pk_bf16_f32 v17, v26, v27
	v_cvt_pk_bf16_f32 v19, v22, v23
	v_lshl_add_u64 v[20:21], v[20:21], 0, v[146:147]
	global_store_dwordx4 v[20:21], v[16:19], off
	s_nop 1
	v_mul_f32_e32 v16, 0xbfb8aa3b, v12
	v_mul_f32_e32 v17, 0xbfb8aa3b, v13
	v_exp_f32_e32 v16, v16
	v_exp_f32_e32 v17, v17
	v_add_f32_e32 v16, 1.0, v16
	v_add_f32_e32 v17, 1.0, v17
	v_rcp_f32_e32 v16, v16
	v_rcp_f32_e32 v17, v17
	s_nop 0
	v_pk_mul_f32 v[12:13], v[12:13], v[16:17]
	s_nop 0
	v_pk_mul_f32 v[8:9], v[8:9], v[12:13]
	v_pk_fma_f32 v[12:13], v[94:95], v[160:161], v[14:15] op_sel:[0,1,0] neg_lo:[1,0,0] neg_hi:[1,0,0]
	s_nop 0
	v_pk_fma_f32 v[12:13], v[12:13], v[162:163], v[98:99] op_sel_hi:[1,0,1]
	s_nop 0
	v_mul_f32_e32 v14, 0xbfb8aa3b, v12
	v_mul_f32_e32 v15, 0xbfb8aa3b, v13
	v_exp_f32_e32 v14, v14
	v_exp_f32_e32 v15, v15
	v_add_f32_e32 v14, 1.0, v14
	v_add_f32_e32 v15, 1.0, v15
	v_rcp_f32_e32 v14, v14
	v_rcp_f32_e32 v15, v15
	s_nop 0
	v_pk_mul_f32 v[12:13], v[12:13], v[14:15]
	s_nop 0
	v_pk_mul_f32 v[10:11], v[10:11], v[12:13]
	v_mul_f32_e32 v12, 0xbfb8aa3b, v4
	v_mul_f32_e32 v13, 0xbfb8aa3b, v5
	v_exp_f32_e32 v12, v12
	v_exp_f32_e32 v13, v13
	v_add_f32_e32 v12, 1.0, v12
	v_add_f32_e32 v13, 1.0, v13
	v_rcp_f32_e32 v12, v12
	v_rcp_f32_e32 v13, v13
	s_nop 0
	v_pk_mul_f32 v[4:5], v[4:5], v[12:13]
	s_nop 0
	v_pk_mul_f32 v[4:5], v[0:1], v[4:5]
	v_pk_fma_f32 v[0:1], v[74:75], v[160:161], v[6:7] op_sel:[0,1,0] neg_lo:[1,0,0] neg_hi:[1,0,0]
	s_nop 0
	v_pk_fma_f32 v[0:1], v[0:1], v[162:163], v[78:79] op_sel_hi:[1,0,1]
	s_nop 0
	v_mul_f32_e32 v6, 0xbfb8aa3b, v0
	v_mul_f32_e32 v7, 0xbfb8aa3b, v1
	v_exp_f32_e32 v6, v6
	v_exp_f32_e32 v7, v7
	v_add_f32_e32 v6, 1.0, v6
	v_add_f32_e32 v7, 1.0, v7
	v_rcp_f32_e32 v6, v6
	v_rcp_f32_e32 v7, v7
	s_nop 0
	v_pk_mul_f32 v[0:1], v[0:1], v[6:7]
	s_nop 0
	v_pk_mul_f32 v[6:7], v[2:3], v[0:1]
	v_cvt_pk_bf16_f32 v2, v4, v5
	v_mad_i64_i32 v[4:5], s[14:15], v206, s1, v[144:145]
	v_lshl_add_u64 v[4:5], v[4:5], 0, s[10:11]
	v_cvt_pk_bf16_f32 v0, v8, v9
	v_cvt_pk_bf16_f32 v1, v10, v11
	v_cvt_pk_bf16_f32 v3, v6, v7
	v_lshl_add_u64 v[4:5], v[4:5], 0, v[146:147]
	s_mov_b64 s[14:15], s[44:45]
	s_mov_b64 s[10:11], s[42:43]
	global_store_dwordx4 v[4:5], v[0:3], off
	s_cbranch_vccz .LBB0_875
	s_waitcnt vmcnt(0)
	s_cmpk_gt_u32 s18, 0xff
	s_cbranch_scc1 .LBB0_882
	s_barrier
